# GEMM tile boundary: counted vmcnt(24) in the first two phases of each tile so the epilogue stores drain under them; epilogue stores in global form
# baseline (speedup 1.0000x reference)
; #define STAGE(bufoff, gbase, voff) do { _Pragma("unroll") for (int _i = 0; _i < 2; ++_i) \
;     __builtin_amdgcn_global_load_lds((const unsigned*)((const char*)(gbase) + (voff)[_i]), (LAS unsigned*)(lds + (bufoff) + ldsw + _i * 8192), 16, 0, 0); } while (0)
; #define WAIT_V(n) asm volatile("s_waitcnt vmcnt(" #n ")" ::: "memory")
; #define BAR __builtin_amdgcn_s_barrier()
; template <int EPI>
; DI void gemm_phase(const int wid_s, const h16* __restrict__ A, const h16* __restrict__ Bt, const int N, const int K, const EpiArgs ea) {
;     ...
;   STAGE(SB(0, 0), cB, voffB); STAGE(SB(0, 1), cB + hstep, voffB); STAGE(SA(0, 0), cA, voffA); STAGE(SA(0, 1), cA + hstep, voffA);
;   if (wr == 1) BAR;
;   WAIT_V(2); BAR;
;   STAGE(SB(1, 0), cB + kstep, voffB); STAGE(SA(1, 0), cA + kstep, voffA); STAGE(SB(1, 1), cB + hstep + kstep, voffB);
;   WAIT_V(6); BAR;
.LBB0_112:
	v_lshrrev_b32_e32 v24, 1, v19
	v_and_b32_e32 v24, 24, v24
	v_and_b32_e32 v23, 15, v19
	v_lshlrev_b32_e32 v25, 1, v24
	v_lshlrev_b32_e32 v19, 2, v19
	v_lshl_or_b32 v5, s7, 6, v23
	v_lshl_or_b32 v23, v23, 6, v25
	s_lshl_b32 s7, s7, 13
	v_and_b32_e32 v19, 32, v19
	v_bitop3_b32 v25, v23, s7, v19 bitop3:0xde
	s_lshl_b32 s7, s8, 5
	s_and_b32 s7, s7, 0x60
	s_add_i32 m0, s22, 0x18000
	v_lshl_add_u64 v[12:13], v[12:13], 0, s[36:37]
	s_lshl_b32 s40, s9, 8
	s_lshl_b32 s8, s7, 7
	s_waitcnt vmcnt(2)
	s_barrier
	global_load_lds_dwordx4 v[12:13], off
	v_lshl_add_u64 v[10:11], v[10:11], 0, s[36:37]
	s_add_i32 m0, s22, 0x1a000
	s_add_i32 s27, s22, 0x8000
	s_add_i32 s30, s22, 0xa000
	global_load_lds_dwordx4 v[10:11], off
	v_lshl_add_u64 v[6:7], v[6:7], 0, s[36:37]
	s_mov_b32 m0, s27
	s_add_u32 s4, s4, 0xb0080
	global_load_lds_dwordx4 v[6:7], off
	v_lshl_add_u64 v[6:7], v[8:9], 0, s[36:37]
	s_mov_b32 m0, s30
	s_addc_u32 s5, s5, 0
	global_load_lds_dwordx4 v[6:7], off
	s_add_i32 m0, s22, 0x1c000
	v_lshl_add_u64 v[6:7], s[4:5], 0, v[0:1]
	global_load_lds_dwordx4 v[6:7], off
	v_lshl_add_u64 v[6:7], s[4:5], 0, v[138:139]
	s_add_i32 m0, s22, 0x1e000
	v_bitop3_b32 v148, v23, s8, v19 bitop3:0xde
	global_load_lds_dwordx4 v[6:7], off
	s_movk_i32 s8, 0xb00
	v_lshrrev_b32_e32 v7, 1, v18
	v_mul_lo_u32 v6, v21, s8
	s_mov_b32 s9, 0xb000
	s_cmpk_lt_u32 s6, 0x100
	v_or_b32_e32 v150, s7, v24
	v_mad_u64_u32 v[6:7], s[6:7], v7, s9, v[6:7]
	v_or_b32_e32 v6, v6, v20
	v_add_lshl_u32 v6, v6, v22, 1
	v_mov_b32_e32 v7, v1
	s_mov_b64 s[10:11], 0xb0080
	v_lshl_add_u64 v[140:141], v[6:7], 0, s[10:11]
	v_lshrrev_b32_e32 v7, 1, v14
	v_mul_lo_u32 v6, v16, s8
	v_mad_u64_u32 v[6:7], s[6:7], v7, s9, v[6:7]
	s_waitcnt vmcnt(0)
	v_or_b32_e32 v6, v6, v15
	v_add_lshl_u32 v6, v6, v17, 1
	v_mov_b32_e32 v7, v1
	s_cselect_b64 s[4:5], -1, 0
	v_lshl_add_u64 v[142:143], v[6:7], 0, s[10:11]
	v_add_u32_e32 v151, 0, v25
	s_mov_b32 s31, s39
	s_mov_b32 s38, s40
	s_barrier
	s_branch .LBB0_115

; #define STAGE(bufoff, gbase, voff) do { _Pragma("unroll") for (int _i = 0; _i < 2; ++_i) \
;     __builtin_amdgcn_global_load_lds((const unsigned*)((const char*)(gbase) + (voff)[_i]), (LAS unsigned*)(lds + (bufoff) + ldsw + _i * 8192), 16, 0, 0); } while (0)
; #define LDA(dst, b, h) do { _Pragma("unroll") for (int m = 0; m < 4; ++m) _Pragma("unroll") for (int k = 0; k < 2; ++k) dst[m][k] = *(const LAS half8*)(lds + SA(b, h) + aoff + m * 2048 + k * 1024); } while (0)
; #define LDB(dst, b, h) do { _Pragma("unroll") for (int n = 0; n < 2; ++n) _Pragma("unroll") for (int k = 0; k < 2; ++k) dst[n][k] = *(const LAS half8*)(lds + SB(b, h) + boff + n * 2048 + k * 1024); } while (0)
; #define MMA(ai, bj, At_, Bt_) do { __builtin_amdgcn_s_setprio(1); \
;     _Pragma("unroll") for (int m = 0; m < 4; ++m) _Pragma("unroll") for (int n = 0; n < 2; ++n) _Pragma("unroll") for (int k = 0; k < 2; ++k) \
;       acc[ai][bj][m][n] = MFMA16(Bt_[n][k], At_[m][k], acc[ai][bj][m][n]); \
;     __builtin_amdgcn_s_setprio(0); } while (0)
; #define WAIT_V(n) asm volatile("s_waitcnt vmcnt(" #n ")" ::: "memory")
; #define WAIT_L(n) asm volatile("s_waitcnt lgkmcnt(" #n ")" ::: "memory")
; #define BAR __builtin_amdgcn_s_barrier()
; #define SCHED __builtin_amdgcn_sched_barrier(0)
; template <int EPI>
; DI void gemm_phase(const int wid_s, const h16* __restrict__ A, const h16* __restrict__ Bt, const int N, const int K, const EpiArgs ea) {
;     ...
;     for (int t = 0; t < nt; t += 2) {
;       const bool last = (t == nt - 2);
;       const char* a1 = cA + (size_t)(t + 1) * kstep;
;       const char* a2 = last ? nA : cA + (size_t)(t + 2) * kstep; const char* b2 = last ? nB : cB + (size_t)(t + 2) * kstep;
;       const char* a3 = a2 + kstep; const char* b3 = b2 + kstep;
;       LDB(B0, 0, 0); LDB(B1, 0, 1); SCHED; LDA(At, 0, 0); STAGE(SA(1, 1), a1 + hstep, voffA);
;       WAIT_V(8); WAIT_L(0); BAR; MMA(0, 0, At, B0); MMA(0, 1, At, B1); BAR; SCHED;
;       LDA(At, 0, 1); STAGE(SB(0, 0), b2, voffB); STAGE(SB(0, 1), b2 + hstep, voffB); STAGE(SA(0, 0), a2, voffA);
;       WAIT_V(8); WAIT_L(0); BAR; MMA(1, 0, At, B0); MMA(1, 1, At, B1); BAR; SCHED;
.LBB0_121:
	s_mul_i32 s8, s31, 0x1600
	s_mul_hi_i32 s9, s31, 0x1600
	s_add_u32 s8, s28, s8
	s_addc_u32 s9, s29, s9
	s_mul_i32 s10, s38, 0x1600
	v_readlane_b32 s16, v250, 58
	s_mul_hi_i32 s11, s38, 0x1600
	s_add_u32 s41, s16, s10
	v_readlane_b32 s16, v250, 61
	s_addc_u32 s42, s16, s11
	v_readlane_b32 s16, v249, 21
	s_add_u32 s43, s16, s14
	v_readlane_b32 s14, v249, 22
	v_mov_b32_e32 v6, 0
	s_addc_u32 s44, s14, s15
	s_mov_b32 s45, -2
	s_add_u32 s14, s12, 0x100
	s_addc_u32 s15, s13, 0
	s_add_i32 s46, 0, 0x10000
	s_cmp_eq_u32 s45, 40
	s_cselect_b32 s19, s9, s15
	s_cselect_b32 s18, s8, s14
	v_add_u32_e32 v177, s46, v148
	s_cselect_b32 s17, s42, s44
	s_cselect_b32 s16, s41, s43
	s_add_i32 s47, 0, 0x14000
	ds_read_b128 v[144:147], v177
	ds_read_b128 v[152:155], v177 offset:1024
	ds_read_b128 v[178:181], v177 offset:2048
	ds_read_b128 v[182:185], v177 offset:3072
	v_add_u32_e32 v177, s47, v148
	ds_read_b128 v[186:189], v177
	ds_read_b128 v[190:193], v177 offset:1024
	ds_read_b128 v[194:197], v177 offset:2048
	ds_read_b128 v[198:201], v177 offset:3072
	v_lshl_add_u64 v[234:235], s[12:13], 0, v[142:143]
	s_add_i32 m0, s22, 0xc000
	ds_read_b128 v[202:205], v151
	ds_read_b128 v[206:209], v151 offset:1024
	ds_read_b128 v[210:213], v151 offset:2048
	ds_read_b128 v[214:217], v151 offset:3072
	ds_read_b128 v[218:221], v151 offset:4096
	ds_read_b128 v[222:225], v151 offset:5120
	ds_read_b128 v[226:229], v151 offset:6144
	ds_read_b128 v[230:233], v151 offset:7168
	global_load_lds_dwordx4 v[234:235], off
	v_lshl_add_u64 v[234:235], s[12:13], 0, v[140:141]
	s_add_i32 m0, s22, 0xe000
	s_nop 0
	global_load_lds_dwordx4 v[234:235], off
	s_waitcnt vmcnt(24)
	s_waitcnt lgkmcnt(0)
	s_barrier
	s_waitcnt lgkmcnt(0)
	v_mfma_f32_16x16x32_f16 v[130:133], v[144:147], v[202:205], 0
	v_mfma_f32_16x16x32_f16 v[126:129], v[178:181], v[202:205], 0
	v_mfma_f32_16x16x32_f16 v[114:117], v[144:147], v[210:213], 0
	v_mfma_f32_16x16x32_f16 v[110:113], v[178:181], v[210:213], 0
	v_mfma_f32_16x16x32_f16 v[98:101], v[144:147], v[218:221], 0
	v_mfma_f32_16x16x32_f16 v[94:97], v[178:181], v[218:221], 0
	v_mfma_f32_16x16x32_f16 v[82:85], v[144:147], v[226:229], 0
	v_mfma_f32_16x16x32_f16 v[78:81], v[178:181], v[226:229], 0
	v_mfma_f32_16x16x32_f16 v[130:133], v[152:155], v[206:209], v[130:133]
	v_mfma_f32_16x16x32_f16 v[126:129], v[182:185], v[206:209], v[126:129]
	v_mfma_f32_16x16x32_f16 v[114:117], v[152:155], v[214:217], v[114:117]
	v_mfma_f32_16x16x32_f16 v[110:113], v[182:185], v[214:217], v[110:113]
	v_mfma_f32_16x16x32_f16 v[98:101], v[152:155], v[222:225], v[98:101]
	v_mfma_f32_16x16x32_f16 v[94:97], v[182:185], v[222:225], v[94:97]
	v_mfma_f32_16x16x32_f16 v[82:85], v[152:155], v[230:233], v[82:85]
	v_mfma_f32_16x16x32_f16 v[78:81], v[182:185], v[230:233], v[78:81]
	v_mfma_f32_16x16x32_f16 v[122:125], v[186:189], v[202:205], 0
	v_mfma_f32_16x16x32_f16 v[118:121], v[194:197], v[202:205], 0
	v_mfma_f32_16x16x32_f16 v[106:109], v[186:189], v[210:213], 0
	v_mfma_f32_16x16x32_f16 v[102:105], v[194:197], v[210:213], 0
	v_mfma_f32_16x16x32_f16 v[90:93], v[186:189], v[218:221], 0
	v_mfma_f32_16x16x32_f16 v[86:89], v[194:197], v[218:221], 0
	v_mfma_f32_16x16x32_f16 v[74:77], v[186:189], v[226:229], 0
	v_mfma_f32_16x16x32_f16 v[70:73], v[194:197], v[226:229], 0
	v_mfma_f32_16x16x32_f16 v[122:125], v[190:193], v[206:209], v[122:125]
	v_mfma_f32_16x16x32_f16 v[118:121], v[198:201], v[206:209], v[118:121]
	v_mfma_f32_16x16x32_f16 v[106:109], v[190:193], v[214:217], v[106:109]
	v_mfma_f32_16x16x32_f16 v[102:105], v[198:201], v[214:217], v[102:105]
	v_mfma_f32_16x16x32_f16 v[90:93], v[190:193], v[222:225], v[90:93]
	v_mfma_f32_16x16x32_f16 v[86:89], v[198:201], v[222:225], v[86:89]
	v_mfma_f32_16x16x32_f16 v[74:77], v[190:193], v[230:233], v[74:77]
	v_mfma_f32_16x16x32_f16 v[70:73], v[198:201], v[230:233], v[70:73]
	s_barrier
	s_add_i32 s12, s46, s21
	v_lshl_add_u64 v[234:235], s[16:17], 0, v[0:1]
	s_mov_b32 m0, s12
	ds_read_b128 v[202:205], v151 offset:16384
	ds_read_b128 v[206:209], v151 offset:17408
	ds_read_b128 v[210:213], v151 offset:18432
	ds_read_b128 v[214:217], v151 offset:19456
	ds_read_b128 v[218:221], v151 offset:20480
	ds_read_b128 v[222:225], v151 offset:21504
	ds_read_b128 v[226:229], v151 offset:22528
	ds_read_b128 v[230:233], v151 offset:23552
	global_load_lds_dwordx4 v[234:235], off
	s_add_i32 m0, s12, 0x2000
	s_add_u32 s12, s16, 0xb0000
	v_lshl_add_u64 v[236:237], s[16:17], 0, v[138:139]
	s_addc_u32 s13, s17, 0
	s_add_i32 s46, s47, s21
	global_load_lds_dwordx4 v[236:237], off
	v_lshl_add_u64 v[238:239], s[12:13], 0, v[0:1]
	s_mov_b32 m0, s46
	v_lshl_add_u64 v[240:241], s[18:19], 0, v[134:135]
	global_load_lds_dwordx4 v[238:239], off
	v_lshl_add_u64 v[238:239], s[12:13], 0, v[138:139]
	s_add_i32 m0, s46, 0x2000
	s_nop 0
	global_load_lds_dwordx4 v[238:239], off
	v_lshl_add_u64 v[238:239], s[18:19], 0, v[2:3]
	s_mov_b32 m0, s22
	s_nop 0
	global_load_lds_dwordx4 v[238:239], off
	s_mov_b32 m0, s23
	s_nop 0
	global_load_lds_dwordx4 v[240:241], off
	s_waitcnt vmcnt(24)
	s_waitcnt lgkmcnt(0)
	s_barrier
; #define STAGE(bufoff, gbase, voff) do { _Pragma("unroll") for (int _i = 0; _i < 2; ++_i) \
;     __builtin_amdgcn_global_load_lds((const unsigned*)((const char*)(gbase) + (voff)[_i]), (LAS unsigned*)(lds + (bufoff) + ldsw + _i * 8192), 16, 0, 0); } while (0)
; #define LDA(dst, b, h) do { _Pragma("unroll") for (int m = 0; m < 4; ++m) _Pragma("unroll") for (int k = 0; k < 2; ++k) dst[m][k] = *(const LAS half8*)(lds + SA(b, h) + aoff + m * 2048 + k * 1024); } while (0)
; #define LDB(dst, b, h) do { _Pragma("unroll") for (int n = 0; n < 2; ++n) _Pragma("unroll") for (int k = 0; k < 2; ++k) dst[n][k] = *(const LAS half8*)(lds + SB(b, h) + boff + n * 2048 + k * 1024); } while (0)
; #define MMA(ai, bj, At_, Bt_) do { __builtin_amdgcn_s_setprio(1); \
;     _Pragma("unroll") for (int m = 0; m < 4; ++m) _Pragma("unroll") for (int n = 0; n < 2; ++n) _Pragma("unroll") for (int k = 0; k < 2; ++k) \
;       acc[ai][bj][m][n] = MFMA16(Bt_[n][k], At_[m][k], acc[ai][bj][m][n]); \
;     __builtin_amdgcn_s_setprio(0); } while (0)
; #define WAIT_V(n) asm volatile("s_waitcnt vmcnt(" #n ")" ::: "memory")
; #define WAIT_L(n) asm volatile("s_waitcnt lgkmcnt(" #n ")" ::: "memory")
; #define BAR __builtin_amdgcn_s_barrier()
; #define SCHED __builtin_amdgcn_sched_barrier(0)
; template <int EPI>
; DI void gemm_phase(const int wid_s, const h16* __restrict__ A, const h16* __restrict__ Bt, const int N, const int K, const EpiArgs ea) {
;     ...
;       LDB(B0, 0, 0); LDB(B1, 0, 1); SCHED; LDA(At, 0, 0); STAGE(SA(1, 1), a1 + hstep, voffA);
;       WAIT_V(8); WAIT_L(0); BAR; MMA(0, 0, At, B0); MMA(0, 1, At, B1); BAR; SCHED;
;       LDA(At, 0, 1); STAGE(SB(0, 0), b2, voffB); STAGE(SB(0, 1), b2 + hstep, voffB); STAGE(SA(0, 0), a2, voffA);
;       WAIT_V(8); WAIT_L(0); BAR; MMA(1, 0, At, B0); MMA(1, 1, At, B1); BAR; SCHED;
;       LDB(B0, 1, 0); LDB(B1, 1, 1); SCHED; LDA(At, 1, 0); STAGE(SA(0, 1), a2 + hstep, voffA);
;       WAIT_V(8); WAIT_L(0); BAR; MMA(0, 0, At, B0); MMA(0, 1, At, B1); BAR; SCHED;
	s_waitcnt lgkmcnt(0)
	v_mfma_f32_16x16x32_f16 v[66:69], v[144:147], v[202:205], 0
	v_mfma_f32_16x16x32_f16 v[62:65], v[178:181], v[202:205], 0
	v_mfma_f32_16x16x32_f16 v[50:53], v[144:147], v[210:213], 0
	v_mfma_f32_16x16x32_f16 v[46:49], v[178:181], v[210:213], 0
	v_mfma_f32_16x16x32_f16 v[34:37], v[144:147], v[218:221], 0
	v_mfma_f32_16x16x32_f16 v[30:33], v[178:181], v[218:221], 0
	v_mfma_f32_16x16x32_f16 v[18:21], v[144:147], v[226:229], 0
	v_mfma_f32_16x16x32_f16 v[14:17], v[178:181], v[226:229], 0
	v_mfma_f32_16x16x32_f16 v[66:69], v[152:155], v[206:209], v[66:69]
	v_mfma_f32_16x16x32_f16 v[62:65], v[182:185], v[206:209], v[62:65]
	v_mfma_f32_16x16x32_f16 v[50:53], v[152:155], v[214:217], v[50:53]
	v_mfma_f32_16x16x32_f16 v[46:49], v[182:185], v[214:217], v[46:49]
	v_mfma_f32_16x16x32_f16 v[34:37], v[152:155], v[222:225], v[34:37]
	v_mfma_f32_16x16x32_f16 v[30:33], v[182:185], v[222:225], v[30:33]
	v_mfma_f32_16x16x32_f16 v[18:21], v[152:155], v[230:233], v[18:21]
	v_mfma_f32_16x16x32_f16 v[14:17], v[182:185], v[230:233], v[14:17]
	v_mfma_f32_16x16x32_f16 v[58:61], v[186:189], v[202:205], 0
	v_mfma_f32_16x16x32_f16 v[54:57], v[194:197], v[202:205], 0
	v_mfma_f32_16x16x32_f16 v[42:45], v[186:189], v[210:213], 0
	v_mfma_f32_16x16x32_f16 v[38:41], v[194:197], v[210:213], 0
	v_mfma_f32_16x16x32_f16 v[26:29], v[186:189], v[218:221], 0
	v_mfma_f32_16x16x32_f16 v[22:25], v[194:197], v[218:221], 0
	v_mfma_f32_16x16x32_f16 v[10:13], v[186:189], v[226:229], 0
	v_mfma_f32_16x16x32_f16 v[6:9], v[194:197], v[226:229], 0
	v_mfma_f32_16x16x32_f16 v[58:61], v[190:193], v[206:209], v[58:61]
	v_mfma_f32_16x16x32_f16 v[54:57], v[198:201], v[206:209], v[54:57]
	v_mfma_f32_16x16x32_f16 v[42:45], v[190:193], v[214:217], v[42:45]
	v_mfma_f32_16x16x32_f16 v[38:41], v[198:201], v[214:217], v[38:41]
	v_mfma_f32_16x16x32_f16 v[26:29], v[190:193], v[222:225], v[26:29]
	v_mfma_f32_16x16x32_f16 v[22:25], v[198:201], v[222:225], v[22:25]
	v_mfma_f32_16x16x32_f16 v[10:13], v[190:193], v[230:233], v[10:13]
	v_mfma_f32_16x16x32_f16 v[6:9], v[198:201], v[230:233], v[6:9]
	s_barrier
	s_add_i32 s46, 0, 0x18000
	v_add_u32_e32 v177, s46, v148
	s_add_i32 s47, 0, 0x1c000
	ds_read_b128 v[144:147], v177
	ds_read_b128 v[152:155], v177 offset:1024
	ds_read_b128 v[178:181], v177 offset:2048
	ds_read_b128 v[182:185], v177 offset:3072
	v_add_u32_e32 v177, s47, v148
	ds_read_b128 v[186:189], v177
	ds_read_b128 v[190:193], v177 offset:1024
	ds_read_b128 v[194:197], v177 offset:2048
	ds_read_b128 v[198:201], v177 offset:3072
	s_add_u32 s12, s18, 0xb0000
	s_addc_u32 s13, s19, 0
	s_mov_b32 m0, s24
	v_lshl_add_u64 v[242:243], s[12:13], 0, v[2:3]
	ds_read_b128 v[202:205], v151 offset:32768
	ds_read_b128 v[206:209], v151 offset:33792
	ds_read_b128 v[210:213], v151 offset:34816
	ds_read_b128 v[214:217], v151 offset:35840
	ds_read_b128 v[218:221], v151 offset:36864
	ds_read_b128 v[222:225], v151 offset:37888
	ds_read_b128 v[226:229], v151 offset:38912
	ds_read_b128 v[230:233], v151 offset:39936
	global_load_lds_dwordx4 v[242:243], off
	v_lshl_add_u64 v[242:243], s[12:13], 0, v[134:135]
	s_mov_b32 m0, s26
	s_nop 0
	global_load_lds_dwordx4 v[242:243], off
	s_waitcnt vmcnt(8)
	s_waitcnt lgkmcnt(0)
	s_barrier
	s_waitcnt lgkmcnt(0)
	v_mfma_f32_16x16x32_f16 v[130:133], v[144:147], v[202:205], v[130:133]
	v_mfma_f32_16x16x32_f16 v[126:129], v[178:181], v[202:205], v[126:129]
	v_mfma_f32_16x16x32_f16 v[114:117], v[144:147], v[210:213], v[114:117]
	v_mfma_f32_16x16x32_f16 v[110:113], v[178:181], v[210:213], v[110:113]
	v_mfma_f32_16x16x32_f16 v[98:101], v[144:147], v[218:221], v[98:101]
	v_mfma_f32_16x16x32_f16 v[94:97], v[178:181], v[218:221], v[94:97]
	v_mfma_f32_16x16x32_f16 v[82:85], v[144:147], v[226:229], v[82:85]
	v_mfma_f32_16x16x32_f16 v[78:81], v[178:181], v[226:229], v[78:81]
	v_mfma_f32_16x16x32_f16 v[130:133], v[152:155], v[206:209], v[130:133]
	v_mfma_f32_16x16x32_f16 v[126:129], v[182:185], v[206:209], v[126:129]
	v_mfma_f32_16x16x32_f16 v[114:117], v[152:155], v[214:217], v[114:117]
	v_mfma_f32_16x16x32_f16 v[110:113], v[182:185], v[214:217], v[110:113]
	v_mfma_f32_16x16x32_f16 v[98:101], v[152:155], v[222:225], v[98:101]
	v_mfma_f32_16x16x32_f16 v[94:97], v[182:185], v[222:225], v[94:97]
	v_mfma_f32_16x16x32_f16 v[82:85], v[152:155], v[230:233], v[82:85]
	v_mfma_f32_16x16x32_f16 v[78:81], v[182:185], v[230:233], v[78:81]
	v_mfma_f32_16x16x32_f16 v[122:125], v[186:189], v[202:205], v[122:125]
	v_mfma_f32_16x16x32_f16 v[118:121], v[194:197], v[202:205], v[118:121]
	v_mfma_f32_16x16x32_f16 v[106:109], v[186:189], v[210:213], v[106:109]
	v_mfma_f32_16x16x32_f16 v[102:105], v[194:197], v[210:213], v[102:105]
	v_mfma_f32_16x16x32_f16 v[90:93], v[186:189], v[218:221], v[90:93]
	v_mfma_f32_16x16x32_f16 v[86:89], v[194:197], v[218:221], v[86:89]
	v_mfma_f32_16x16x32_f16 v[74:77], v[186:189], v[226:229], v[74:77]
	v_mfma_f32_16x16x32_f16 v[70:73], v[194:197], v[226:229], v[70:73]
	v_mfma_f32_16x16x32_f16 v[122:125], v[190:193], v[206:209], v[122:125]
	v_mfma_f32_16x16x32_f16 v[118:121], v[198:201], v[206:209], v[118:121]
	v_mfma_f32_16x16x32_f16 v[106:109], v[190:193], v[214:217], v[106:109]
	v_mfma_f32_16x16x32_f16 v[102:105], v[198:201], v[214:217], v[102:105]
	v_mfma_f32_16x16x32_f16 v[90:93], v[190:193], v[222:225], v[90:93]
	v_mfma_f32_16x16x32_f16 v[86:89], v[198:201], v[222:225], v[86:89]
	v_mfma_f32_16x16x32_f16 v[74:77], v[190:193], v[230:233], v[74:77]
	v_mfma_f32_16x16x32_f16 v[70:73], v[198:201], v[230:233], v[70:73]
	s_barrier
; #define STAGE(bufoff, gbase, voff) do { _Pragma("unroll") for (int _i = 0; _i < 2; ++_i) \
;     __builtin_amdgcn_global_load_lds((const unsigned*)((const char*)(gbase) + (voff)[_i]), (LAS unsigned*)(lds + (bufoff) + ldsw + _i * 8192), 16, 0, 0); } while (0)
; #define LDA(dst, b, h) do { _Pragma("unroll") for (int m = 0; m < 4; ++m) _Pragma("unroll") for (int k = 0; k < 2; ++k) dst[m][k] = *(const LAS half8*)(lds + SA(b, h) + aoff + m * 2048 + k * 1024); } while (0)
; #define LDB(dst, b, h) do { _Pragma("unroll") for (int n = 0; n < 2; ++n) _Pragma("unroll") for (int k = 0; k < 2; ++k) dst[n][k] = *(const LAS half8*)(lds + SB(b, h) + boff + n * 2048 + k * 1024); } while (0)
; #define MMA(ai, bj, At_, Bt_) do { __builtin_amdgcn_s_setprio(1); \
;     _Pragma("unroll") for (int m = 0; m < 4; ++m) _Pragma("unroll") for (int n = 0; n < 2; ++n) _Pragma("unroll") for (int k = 0; k < 2; ++k) \
;       acc[ai][bj][m][n] = MFMA16(Bt_[n][k], At_[m][k], acc[ai][bj][m][n]); \
;     __builtin_amdgcn_s_setprio(0); } while (0)
; #define WAIT_V(n) asm volatile("s_waitcnt vmcnt(" #n ")" ::: "memory")
; #define BAR __builtin_amdgcn_s_barrier()
; template <int EPI>
; DI void gemm_phase(const int wid_s, const h16* __restrict__ A, const h16* __restrict__ Bt, const int N, const int K, const EpiArgs ea) {
;     ...
;     for (int t = 0; t < nt; t += 2) {
;       const bool last = (t == nt - 2);
;       const char* a1 = cA + (size_t)(t + 1) * kstep;
;       const char* a2 = last ? nA : cA + (size_t)(t + 2) * kstep; const char* b2 = last ? nB : cB + (size_t)(t + 2) * kstep;
;       const char* a3 = a2 + kstep; const char* b3 = b2 + kstep;
;       LDB(B0, 0, 0); LDB(B1, 0, 1); SCHED; LDA(At, 0, 0); STAGE(SA(1, 1), a1 + hstep, voffA);
;       WAIT_V(8); WAIT_L(0); BAR; MMA(0, 0, At, B0); MMA(0, 1, At, B1); BAR; SCHED;
;       LDA(At, 0, 1); STAGE(SB(0, 0), b2, voffB); STAGE(SB(0, 1), b2 + hstep, voffB); STAGE(SA(0, 0), a2, voffA);
;       WAIT_V(8); WAIT_L(0); BAR; MMA(1, 0, At, B0); MMA(1, 1, At, B1); BAR; SCHED;
;       LDB(B0, 1, 0); LDB(B1, 1, 1); SCHED; LDA(At, 1, 0); STAGE(SA(0, 1), a2 + hstep, voffA);
;       WAIT_V(8); WAIT_L(0); BAR; MMA(0, 0, At, B0); MMA(0, 1, At, B1); BAR; SCHED;
;       LDA(At, 1, 1); STAGE(SB(1, 0), b3, voffB); STAGE(SB(1, 1), b3 + hstep, voffB); STAGE(SA(1, 0), a3, voffA);
;       WAIT_V(8); WAIT_L(0); BAR; MMA(1, 0, At, B0); MMA(1, 1, At, B1); BAR; SCHED;
	s_add_i32 s12, s46, s21
	v_lshl_add_u64 v[234:235], v[234:235], 0, s[36:37]
	s_mov_b32 m0, s12
	ds_read_b128 v[202:205], v151 offset:49152
	ds_read_b128 v[206:209], v151 offset:50176
	ds_read_b128 v[210:213], v151 offset:51200
	ds_read_b128 v[214:217], v151 offset:52224
	ds_read_b128 v[218:221], v151 offset:53248
	ds_read_b128 v[222:225], v151 offset:54272
	ds_read_b128 v[226:229], v151 offset:55296
	ds_read_b128 v[230:233], v151 offset:56320
	global_load_lds_dwordx4 v[234:235], off
	s_add_i32 m0, s12, 0x2000
	s_add_u32 s12, s16, 0xb0080
	v_lshl_add_u64 v[234:235], v[236:237], 0, s[36:37]
	s_addc_u32 s13, s17, 0
	s_add_i32 s16, s47, s21
	global_load_lds_dwordx4 v[234:235], off
	v_lshl_add_u64 v[234:235], s[12:13], 0, v[0:1]
	s_mov_b32 m0, s16
	s_nop 0
	global_load_lds_dwordx4 v[234:235], off
	v_lshl_add_u64 v[234:235], s[12:13], 0, v[138:139]
	s_add_i32 m0, s16, 0x2000
	s_nop 0
	global_load_lds_dwordx4 v[234:235], off
	v_lshl_add_u64 v[234:235], v[238:239], 0, s[36:37]
	s_mov_b32 m0, s27
	s_nop 0
	global_load_lds_dwordx4 v[234:235], off
	v_lshl_add_u64 v[234:235], v[240:241], 0, s[36:37]
	s_mov_b32 m0, s30
	s_nop 0
	global_load_lds_dwordx4 v[234:235], off
	s_waitcnt vmcnt(8)
	s_waitcnt lgkmcnt(0)
	s_barrier
	s_waitcnt lgkmcnt(0)
	v_mfma_f32_16x16x32_f16 v[66:69], v[144:147], v[202:205], v[66:69]
	v_mfma_f32_16x16x32_f16 v[62:65], v[178:181], v[202:205], v[62:65]
	v_mfma_f32_16x16x32_f16 v[50:53], v[144:147], v[210:213], v[50:53]
	v_mfma_f32_16x16x32_f16 v[46:49], v[178:181], v[210:213], v[46:49]
	v_mfma_f32_16x16x32_f16 v[34:37], v[144:147], v[218:221], v[34:37]
	v_mfma_f32_16x16x32_f16 v[30:33], v[178:181], v[218:221], v[30:33]
	v_mfma_f32_16x16x32_f16 v[18:21], v[144:147], v[226:229], v[18:21]
	v_mfma_f32_16x16x32_f16 v[14:17], v[178:181], v[226:229], v[14:17]
	v_mfma_f32_16x16x32_f16 v[66:69], v[152:155], v[206:209], v[66:69]
	v_mfma_f32_16x16x32_f16 v[62:65], v[182:185], v[206:209], v[62:65]
	v_mfma_f32_16x16x32_f16 v[50:53], v[152:155], v[214:217], v[50:53]
	v_mfma_f32_16x16x32_f16 v[46:49], v[182:185], v[214:217], v[46:49]
	v_mfma_f32_16x16x32_f16 v[34:37], v[152:155], v[222:225], v[34:37]
	v_mfma_f32_16x16x32_f16 v[30:33], v[182:185], v[222:225], v[30:33]
	v_mfma_f32_16x16x32_f16 v[18:21], v[152:155], v[230:233], v[18:21]
	v_mfma_f32_16x16x32_f16 v[14:17], v[182:185], v[230:233], v[14:17]
	v_mfma_f32_16x16x32_f16 v[58:61], v[186:189], v[202:205], v[58:61]
	v_mfma_f32_16x16x32_f16 v[54:57], v[194:197], v[202:205], v[54:57]
	v_mfma_f32_16x16x32_f16 v[42:45], v[186:189], v[210:213], v[42:45]
	v_mfma_f32_16x16x32_f16 v[38:41], v[194:197], v[210:213], v[38:41]
	v_mfma_f32_16x16x32_f16 v[26:29], v[186:189], v[218:221], v[26:29]
	v_mfma_f32_16x16x32_f16 v[22:25], v[194:197], v[218:221], v[22:25]
	v_mfma_f32_16x16x32_f16 v[10:13], v[186:189], v[226:229], v[10:13]
	v_mfma_f32_16x16x32_f16 v[6:9], v[194:197], v[226:229], v[6:9]
	v_mfma_f32_16x16x32_f16 v[58:61], v[190:193], v[206:209], v[58:61]
	v_mfma_f32_16x16x32_f16 v[54:57], v[198:201], v[206:209], v[54:57]
	v_mfma_f32_16x16x32_f16 v[42:45], v[190:193], v[214:217], v[42:45]
	v_mfma_f32_16x16x32_f16 v[38:41], v[198:201], v[214:217], v[38:41]
	v_mfma_f32_16x16x32_f16 v[26:29], v[190:193], v[222:225], v[26:29]
	v_mfma_f32_16x16x32_f16 v[22:25], v[198:201], v[222:225], v[22:25]
	v_mfma_f32_16x16x32_f16 v[10:13], v[190:193], v[230:233], v[10:13]
	v_mfma_f32_16x16x32_f16 v[6:9], v[198:201], v[230:233], v[6:9]
	s_barrier
	s_add_i32 s45, s45, 2
	s_add_u32 s43, s43, 0x100
	s_addc_u32 s44, s44, 0
	s_cmp_gt_u32 s45, 41
	s_mov_b64 s[12:13], s[14:15]

; #define STAGE(bufoff, gbase, voff) do { _Pragma("unroll") for (int _i = 0; _i < 2; ++_i) \
;     __builtin_amdgcn_global_load_lds((const unsigned*)((const char*)(gbase) + (voff)[_i]), (LAS unsigned*)(lds + (bufoff) + ldsw + _i * 8192), 16, 0, 0); } while (0)
; #define WAIT_V(n) asm volatile("s_waitcnt vmcnt(" #n ")" ::: "memory")
; #define BAR __builtin_amdgcn_s_barrier()
; template <int EPI>
; DI void gemm_phase(const int wid_s, const h16* __restrict__ A, const h16* __restrict__ Bt, const int N, const int K, const EpiArgs ea) {
;     ...
;   STAGE(SB(0, 0), cB, voffB); STAGE(SB(0, 1), cB + hstep, voffB); STAGE(SA(0, 0), cA, voffA); STAGE(SA(0, 1), cA + hstep, voffA);
;   if (wr == 1) BAR;
;   WAIT_V(2); BAR;
;   STAGE(SB(1, 0), cB + kstep, voffB); STAGE(SA(1, 0), cA + kstep, voffA); STAGE(SB(1, 1), cB + hstep + kstep, voffB);
;   WAIT_V(6); BAR;
.LBB0_135:
	s_lshl_b32 s7, s7, 5
	v_and_b32_e32 v21, 15, v20
	s_and_b32 s39, s7, 0x60
	s_add_i32 m0, s17, 0x18000
	v_lshl_add_u64 v[6:7], v[6:7], 0, s[36:37]
	v_lshl_or_b32 v5, s8, 6, v21
	s_lshl_b32 s8, s8, 13
	s_lshl_b32 s7, s39, 7
	s_waitcnt vmcnt(2)
	s_barrier
	global_load_lds_dwordx4 v[6:7], off
	v_lshl_add_u64 v[6:7], v[8:9], 0, s[36:37]
	s_add_i32 m0, s17, 0x1a000
	s_add_i32 s40, s17, 0x8000
	s_add_i32 s41, s17, 0xa000
	global_load_lds_dwordx4 v[6:7], off
	v_lshl_add_u64 v[6:7], v[10:11], 0, s[36:37]
	s_mov_b32 m0, s40
	s_add_u32 s4, s4, 0x40080
	global_load_lds_dwordx4 v[6:7], off
	v_lshl_add_u64 v[6:7], v[12:13], 0, s[36:37]
	s_mov_b32 m0, s41
	s_addc_u32 s5, s5, 0
	global_load_lds_dwordx4 v[6:7], off
	s_add_i32 m0, s17, 0x1c000
	v_lshl_add_u64 v[6:7], s[4:5], 0, v[0:1]
	global_load_lds_dwordx4 v[6:7], off
	v_lshl_add_u64 v[6:7], s[4:5], 0, v[2:3]
	s_add_i32 m0, s17, 0x1e000
	v_bfe_u32 v22, v20, 4, 2
	global_load_lds_dwordx4 v[6:7], off
	v_lshlrev_b32_e32 v6, 14, v14
	v_lshlrev_b32_e32 v23, 4, v22
	v_lshlrev_b32_e32 v20, 2, v20
	v_and_b32_e32 v6, 0xffff8000, v6
	v_lshl_or_b32 v21, v21, 6, v23
	v_and_b32_e32 v20, 32, v20
	v_lshl_add_u32 v6, v15, 11, v6
	v_and_b32_e32 v7, 1, v14
	v_bitop3_b32 v148, v21, s7, v20 bitop3:0xde
	s_cmpk_lt_u32 s6, 0x100
	v_lshl_or_b32 v6, v7, 6, v6
	v_readlane_b32 s6, v249, 25
	v_lshl_add_u32 v6, v16, 1, v6
	v_mov_b32_e32 v7, v1
	v_readlane_b32 s7, v249, 26
	s_waitcnt vmcnt(0)
	v_bitop3_b32 v23, v21, s8, v20 bitop3:0xde
	s_cselect_b64 s[4:5], -1, 0
	v_lshl_add_u64 v[140:141], s[6:7], 0, v[6:7]
	v_lshlrev_b32_e32 v6, 14, v18
	v_and_b32_e32 v6, 0xffff8000, v6
	v_lshl_add_u32 v6, v17, 11, v6
	v_and_b32_e32 v7, 1, v18
	v_lshl_or_b32 v6, v7, 6, v6
	v_lshl_add_u32 v6, v19, 1, v6
	v_mov_b32_e32 v7, v1
	v_lshlrev_b32_e32 v150, 2, v22
	v_lshl_add_u64 v[142:143], s[6:7], 0, v[6:7]
	v_add_u32_e32 v151, 0, v23
	s_barrier
	s_branch .LBB0_138

; #define STAGE(bufoff, gbase, voff) do { _Pragma("unroll") for (int _i = 0; _i < 2; ++_i) \
;     __builtin_amdgcn_global_load_lds((const unsigned*)((const char*)(gbase) + (voff)[_i]), (LAS unsigned*)(lds + (bufoff) + ldsw + _i * 8192), 16, 0, 0); } while (0)
; #define LDA(dst, b, h) do { _Pragma("unroll") for (int m = 0; m < 4; ++m) _Pragma("unroll") for (int k = 0; k < 2; ++k) dst[m][k] = *(const LAS half8*)(lds + SA(b, h) + aoff + m * 2048 + k * 1024); } while (0)
; #define LDB(dst, b, h) do { _Pragma("unroll") for (int n = 0; n < 2; ++n) _Pragma("unroll") for (int k = 0; k < 2; ++k) dst[n][k] = *(const LAS half8*)(lds + SB(b, h) + boff + n * 2048 + k * 1024); } while (0)
; #define MMA(ai, bj, At_, Bt_) do { __builtin_amdgcn_s_setprio(1); \
;     _Pragma("unroll") for (int m = 0; m < 4; ++m) _Pragma("unroll") for (int n = 0; n < 2; ++n) _Pragma("unroll") for (int k = 0; k < 2; ++k) \
;       acc[ai][bj][m][n] = MFMA16(Bt_[n][k], At_[m][k], acc[ai][bj][m][n]); \
;     __builtin_amdgcn_s_setprio(0); } while (0)
; #define WAIT_V(n) asm volatile("s_waitcnt vmcnt(" #n ")" ::: "memory")
; #define WAIT_L(n) asm volatile("s_waitcnt lgkmcnt(" #n ")" ::: "memory")
; #define BAR __builtin_amdgcn_s_barrier()
; template <int EPI>
; DI void gemm_phase(const int wid_s, const h16* __restrict__ A, const h16* __restrict__ Bt, const int N, const int K, const EpiArgs ea) {
;     ...
;     const int Ln = L + (int)gridDim.x;
;     const bool has_next = Ln < nwg;
;     int nbrow = brow, nbcol = bcol;
;     if (has_next) TILE_RC(Ln, nbrow, nbcol);
;     const char* nA = (const char*)A + (size_t)nbrow * K * 2;
;     const char* nB = (const char*)Bt + (size_t)nbcol * K * 2;
;     for (int t = 0; t < nt; t += 2) {
;       const bool last = (t == nt - 2);
;       const char* a1 = cA + (size_t)(t + 1) * kstep;
;       const char* a2 = last ? nA : cA + (size_t)(t + 2) * kstep; const char* b2 = last ? nB : cB + (size_t)(t + 2) * kstep;
;       const char* a3 = a2 + kstep; const char* b3 = b2 + kstep;
;       LDB(B0, 0, 0); LDB(B1, 0, 1); SCHED; LDA(At, 0, 0); STAGE(SA(1, 1), a1 + hstep, voffA);
;       WAIT_V(8); WAIT_L(0); BAR; MMA(0, 0, At, B0); MMA(0, 1, At, B1); BAR; SCHED;
;       LDA(At, 0, 1); STAGE(SB(0, 0), b2, voffB); STAGE(SB(0, 1), b2 + hstep, voffB); STAGE(SA(0, 0), a2, voffA);
;       WAIT_V(8); WAIT_L(0); BAR; MMA(1, 0, At, B0); MMA(1, 1, At, B1); BAR; SCHED;
.LBB0_140:
	s_ashr_i32 s9, s8, 31
	s_lshl_b64 s[12:13], s[8:9], 11
	s_add_u32 s9, s92, s12
	s_addc_u32 s42, s93, s13
	s_ashr_i32 s11, s10, 31
	s_lshl_b64 s[14:15], s[10:11], 11
	v_readlane_b32 s11, v250, 62
	s_add_u32 s11, s11, s14
	v_readlane_b32 s26, v249, 1
	s_addc_u32 s43, s26, s15
	v_readlane_b32 s26, v249, 23
	s_add_u32 s44, s26, s22
	v_readlane_b32 s22, v249, 24
	s_addc_u32 s45, s22, s23
	s_add_u32 s46, s86, s20
	v_mov_b32_e32 v6, 0
	v_lshl_add_u64 v[144:145], v[140:141], 0, s[20:21]
	v_lshl_add_u64 v[146:147], v[142:143], 0, s[20:21]
	s_addc_u32 s47, s87, s21
	s_mov_b32 s48, -2
	s_mov_b64 s[20:21], 0
	s_add_u32 s22, s46, s20
	s_addc_u32 s23, s47, s21
	s_add_u32 s22, s22, 0x520e100
	s_addc_u32 s23, s23, 0
	s_add_u32 s49, s44, s20
	s_addc_u32 s50, s45, s21
	s_add_i32 s51, 0, 0x10000
	s_cmpk_eq_i32 s20, 0x700
	s_cselect_b32 s27, s42, s23
	s_cselect_b32 s26, s9, s22
	v_add_u32_e32 v177, s51, v148
	s_cselect_b32 s23, s43, s50
	s_cselect_b32 s22, s11, s49
	s_add_i32 s49, 0, 0x14000
	ds_read_b128 v[152:155], v177
	ds_read_b128 v[178:181], v177 offset:1024
	ds_read_b128 v[182:185], v177 offset:2048
	ds_read_b128 v[186:189], v177 offset:3072
	v_add_u32_e32 v177, s49, v148
	ds_read_b128 v[190:193], v177
	ds_read_b128 v[194:197], v177 offset:1024
	ds_read_b128 v[198:201], v177 offset:2048
	ds_read_b128 v[202:205], v177 offset:3072
	v_lshl_add_u64 v[238:239], v[146:147], 0, s[20:21]
	s_add_i32 m0, s17, 0xc000
	ds_read_b128 v[206:209], v151
	ds_read_b128 v[210:213], v151 offset:1024
	ds_read_b128 v[214:217], v151 offset:2048
	ds_read_b128 v[218:221], v151 offset:3072
	ds_read_b128 v[222:225], v151 offset:4096
	ds_read_b128 v[226:229], v151 offset:5120
	ds_read_b128 v[230:233], v151 offset:6144
	ds_read_b128 v[234:237], v151 offset:7168
	global_load_lds_dwordx4 v[238:239], off
	v_lshl_add_u64 v[238:239], v[144:145], 0, s[20:21]
	s_add_i32 m0, s17, 0xe000
	s_nop 0
	global_load_lds_dwordx4 v[238:239], off
	s_waitcnt vmcnt(24)
	s_waitcnt lgkmcnt(0)
	s_barrier
	s_waitcnt lgkmcnt(0)
	v_mfma_f32_16x16x32_f16 v[130:133], v[152:155], v[206:209], 0
	v_mfma_f32_16x16x32_f16 v[126:129], v[182:185], v[206:209], 0
	v_mfma_f32_16x16x32_f16 v[114:117], v[152:155], v[214:217], 0
	v_mfma_f32_16x16x32_f16 v[110:113], v[182:185], v[214:217], 0
	v_mfma_f32_16x16x32_f16 v[98:101], v[152:155], v[222:225], 0
	v_mfma_f32_16x16x32_f16 v[94:97], v[182:185], v[222:225], 0
	v_mfma_f32_16x16x32_f16 v[82:85], v[152:155], v[230:233], 0
	v_mfma_f32_16x16x32_f16 v[78:81], v[182:185], v[230:233], 0
	v_mfma_f32_16x16x32_f16 v[130:133], v[178:181], v[210:213], v[130:133]
	v_mfma_f32_16x16x32_f16 v[126:129], v[186:189], v[210:213], v[126:129]
	v_mfma_f32_16x16x32_f16 v[114:117], v[178:181], v[218:221], v[114:117]
	v_mfma_f32_16x16x32_f16 v[110:113], v[186:189], v[218:221], v[110:113]
	v_mfma_f32_16x16x32_f16 v[98:101], v[178:181], v[226:229], v[98:101]
	v_mfma_f32_16x16x32_f16 v[94:97], v[186:189], v[226:229], v[94:97]
	v_mfma_f32_16x16x32_f16 v[82:85], v[178:181], v[234:237], v[82:85]
	v_mfma_f32_16x16x32_f16 v[78:81], v[186:189], v[234:237], v[78:81]
	v_mfma_f32_16x16x32_f16 v[122:125], v[190:193], v[206:209], 0
	v_mfma_f32_16x16x32_f16 v[118:121], v[198:201], v[206:209], 0
	v_mfma_f32_16x16x32_f16 v[106:109], v[190:193], v[214:217], 0
	v_mfma_f32_16x16x32_f16 v[102:105], v[198:201], v[214:217], 0
	v_mfma_f32_16x16x32_f16 v[90:93], v[190:193], v[222:225], 0
	v_mfma_f32_16x16x32_f16 v[86:89], v[198:201], v[222:225], 0
	v_mfma_f32_16x16x32_f16 v[74:77], v[190:193], v[230:233], 0
	v_mfma_f32_16x16x32_f16 v[70:73], v[198:201], v[230:233], 0
	v_mfma_f32_16x16x32_f16 v[122:125], v[194:197], v[210:213], v[122:125]
	v_mfma_f32_16x16x32_f16 v[118:121], v[202:205], v[210:213], v[118:121]
	v_mfma_f32_16x16x32_f16 v[106:109], v[194:197], v[218:221], v[106:109]
	v_mfma_f32_16x16x32_f16 v[102:105], v[202:205], v[218:221], v[102:105]
	v_mfma_f32_16x16x32_f16 v[90:93], v[194:197], v[226:229], v[90:93]
	v_mfma_f32_16x16x32_f16 v[86:89], v[202:205], v[226:229], v[86:89]
	v_mfma_f32_16x16x32_f16 v[74:77], v[194:197], v[234:237], v[74:77]
	v_mfma_f32_16x16x32_f16 v[70:73], v[202:205], v[234:237], v[70:73]
	s_barrier
	s_add_i32 s50, s51, s30
	v_lshl_add_u64 v[238:239], s[22:23], 0, v[0:1]
	s_mov_b32 m0, s50
	ds_read_b128 v[206:209], v151 offset:16384
	ds_read_b128 v[210:213], v151 offset:17408
	ds_read_b128 v[214:217], v151 offset:18432
	ds_read_b128 v[218:221], v151 offset:19456
	ds_read_b128 v[222:225], v151 offset:20480
	ds_read_b128 v[226:229], v151 offset:21504
	ds_read_b128 v[230:233], v151 offset:22528
	ds_read_b128 v[234:237], v151 offset:23552
	global_load_lds_dwordx4 v[238:239], off
	s_add_i32 m0, s50, 0x2000
	s_add_u32 s50, s22, 0x40000
	v_lshl_add_u64 v[240:241], s[22:23], 0, v[2:3]
	s_addc_u32 s51, s23, 0
	s_add_i32 s49, s49, s30
	global_load_lds_dwordx4 v[240:241], off
	v_lshl_add_u64 v[242:243], s[50:51], 0, v[0:1]
	s_mov_b32 m0, s49
	v_lshl_add_u64 v[244:245], s[26:27], 0, v[134:135]
	global_load_lds_dwordx4 v[242:243], off
	v_lshl_add_u64 v[242:243], s[50:51], 0, v[2:3]
	s_add_i32 m0, s49, 0x2000
	s_nop 0
	global_load_lds_dwordx4 v[242:243], off
	v_lshl_add_u64 v[242:243], s[26:27], 0, v[138:139]
	s_mov_b32 m0, s17
	s_nop 0
	global_load_lds_dwordx4 v[242:243], off
	s_mov_b32 m0, s19
	s_nop 0
	global_load_lds_dwordx4 v[244:245], off
	s_waitcnt vmcnt(24)
	s_waitcnt lgkmcnt(0)
	s_barrier
; #define STAGE(bufoff, gbase, voff) do { _Pragma("unroll") for (int _i = 0; _i < 2; ++_i) \
;     __builtin_amdgcn_global_load_lds((const unsigned*)((const char*)(gbase) + (voff)[_i]), (LAS unsigned*)(lds + (bufoff) + ldsw + _i * 8192), 16, 0, 0); } while (0)
; #define LDA(dst, b, h) do { _Pragma("unroll") for (int m = 0; m < 4; ++m) _Pragma("unroll") for (int k = 0; k < 2; ++k) dst[m][k] = *(const LAS half8*)(lds + SA(b, h) + aoff + m * 2048 + k * 1024); } while (0)
; #define LDB(dst, b, h) do { _Pragma("unroll") for (int n = 0; n < 2; ++n) _Pragma("unroll") for (int k = 0; k < 2; ++k) dst[n][k] = *(const LAS half8*)(lds + SB(b, h) + boff + n * 2048 + k * 1024); } while (0)
; #define MMA(ai, bj, At_, Bt_) do { __builtin_amdgcn_s_setprio(1); \
;     _Pragma("unroll") for (int m = 0; m < 4; ++m) _Pragma("unroll") for (int n = 0; n < 2; ++n) _Pragma("unroll") for (int k = 0; k < 2; ++k) \
;       acc[ai][bj][m][n] = MFMA16(Bt_[n][k], At_[m][k], acc[ai][bj][m][n]); \
;     __builtin_amdgcn_s_setprio(0); } while (0)
; #define WAIT_V(n) asm volatile("s_waitcnt vmcnt(" #n ")" ::: "memory")
; #define WAIT_L(n) asm volatile("s_waitcnt lgkmcnt(" #n ")" ::: "memory")
; #define BAR __builtin_amdgcn_s_barrier()
; #define SCHED __builtin_amdgcn_sched_barrier(0)
; template <int EPI>
; DI void gemm_phase(const int wid_s, const h16* __restrict__ A, const h16* __restrict__ Bt, const int N, const int K, const EpiArgs ea) {
;     ...
;       WAIT_V(8); WAIT_L(0); BAR; MMA(1, 0, At, B0); MMA(1, 1, At, B1); BAR; SCHED;
;       LDB(B0, 1, 0); LDB(B1, 1, 1); SCHED; LDA(At, 1, 0); STAGE(SA(0, 1), a2 + hstep, voffA);
;       WAIT_V(8); WAIT_L(0); BAR; MMA(0, 0, At, B0); MMA(0, 1, At, B1); BAR; SCHED;
	s_waitcnt lgkmcnt(0)
	v_mfma_f32_16x16x32_f16 v[66:69], v[152:155], v[206:209], 0
	v_mfma_f32_16x16x32_f16 v[62:65], v[182:185], v[206:209], 0
	v_mfma_f32_16x16x32_f16 v[50:53], v[152:155], v[214:217], 0
	v_mfma_f32_16x16x32_f16 v[46:49], v[182:185], v[214:217], 0
	v_mfma_f32_16x16x32_f16 v[34:37], v[152:155], v[222:225], 0
	v_mfma_f32_16x16x32_f16 v[30:33], v[182:185], v[222:225], 0
	v_mfma_f32_16x16x32_f16 v[18:21], v[152:155], v[230:233], 0
	v_mfma_f32_16x16x32_f16 v[14:17], v[182:185], v[230:233], 0
	v_mfma_f32_16x16x32_f16 v[66:69], v[178:181], v[210:213], v[66:69]
	v_mfma_f32_16x16x32_f16 v[62:65], v[186:189], v[210:213], v[62:65]
	v_mfma_f32_16x16x32_f16 v[50:53], v[178:181], v[218:221], v[50:53]
	v_mfma_f32_16x16x32_f16 v[46:49], v[186:189], v[218:221], v[46:49]
	v_mfma_f32_16x16x32_f16 v[34:37], v[178:181], v[226:229], v[34:37]
	v_mfma_f32_16x16x32_f16 v[30:33], v[186:189], v[226:229], v[30:33]
	v_mfma_f32_16x16x32_f16 v[18:21], v[178:181], v[234:237], v[18:21]
	v_mfma_f32_16x16x32_f16 v[14:17], v[186:189], v[234:237], v[14:17]
	v_mfma_f32_16x16x32_f16 v[58:61], v[190:193], v[206:209], 0
	v_mfma_f32_16x16x32_f16 v[54:57], v[198:201], v[206:209], 0
	v_mfma_f32_16x16x32_f16 v[42:45], v[190:193], v[214:217], 0
	v_mfma_f32_16x16x32_f16 v[38:41], v[198:201], v[214:217], 0
	v_mfma_f32_16x16x32_f16 v[26:29], v[190:193], v[222:225], 0
	v_mfma_f32_16x16x32_f16 v[22:25], v[198:201], v[222:225], 0
	v_mfma_f32_16x16x32_f16 v[10:13], v[190:193], v[230:233], 0
	v_mfma_f32_16x16x32_f16 v[6:9], v[198:201], v[230:233], 0
	v_mfma_f32_16x16x32_f16 v[58:61], v[194:197], v[210:213], v[58:61]
	v_mfma_f32_16x16x32_f16 v[54:57], v[202:205], v[210:213], v[54:57]
	v_mfma_f32_16x16x32_f16 v[42:45], v[194:197], v[218:221], v[42:45]
	v_mfma_f32_16x16x32_f16 v[38:41], v[202:205], v[218:221], v[38:41]
	v_mfma_f32_16x16x32_f16 v[26:29], v[194:197], v[226:229], v[26:29]
	v_mfma_f32_16x16x32_f16 v[22:25], v[202:205], v[226:229], v[22:25]
	v_mfma_f32_16x16x32_f16 v[10:13], v[194:197], v[234:237], v[10:13]
	v_mfma_f32_16x16x32_f16 v[6:9], v[202:205], v[234:237], v[6:9]
	s_barrier
	s_add_i32 s49, 0, 0x18000
	v_add_u32_e32 v177, s49, v148
	s_add_i32 s50, 0, 0x1c000
	ds_read_b128 v[152:155], v177
	ds_read_b128 v[178:181], v177 offset:1024
	ds_read_b128 v[182:185], v177 offset:2048
	ds_read_b128 v[186:189], v177 offset:3072
	v_add_u32_e32 v177, s50, v148
	ds_read_b128 v[190:193], v177
	ds_read_b128 v[194:197], v177 offset:1024
	ds_read_b128 v[198:201], v177 offset:2048
	ds_read_b128 v[202:205], v177 offset:3072
	s_add_u32 s26, s26, 0x40000
	s_addc_u32 s27, s27, 0
	s_mov_b32 m0, s31
	v_lshl_add_u64 v[246:247], s[26:27], 0, v[138:139]
	ds_read_b128 v[206:209], v151 offset:32768
	ds_read_b128 v[210:213], v151 offset:33792
	ds_read_b128 v[214:217], v151 offset:34816
	ds_read_b128 v[218:221], v151 offset:35840
	ds_read_b128 v[222:225], v151 offset:36864
	ds_read_b128 v[226:229], v151 offset:37888
	ds_read_b128 v[230:233], v151 offset:38912
	ds_read_b128 v[234:237], v151 offset:39936
	global_load_lds_dwordx4 v[246:247], off
	v_lshl_add_u64 v[246:247], s[26:27], 0, v[134:135]
	s_mov_b32 m0, s38
	s_nop 0
	global_load_lds_dwordx4 v[246:247], off
	s_waitcnt vmcnt(8)
	s_waitcnt lgkmcnt(0)
	s_barrier
	s_waitcnt lgkmcnt(0)
	v_mfma_f32_16x16x32_f16 v[130:133], v[152:155], v[206:209], v[130:133]
	v_mfma_f32_16x16x32_f16 v[126:129], v[182:185], v[206:209], v[126:129]
	v_mfma_f32_16x16x32_f16 v[114:117], v[152:155], v[214:217], v[114:117]
	v_mfma_f32_16x16x32_f16 v[110:113], v[182:185], v[214:217], v[110:113]
	v_mfma_f32_16x16x32_f16 v[98:101], v[152:155], v[222:225], v[98:101]
	v_mfma_f32_16x16x32_f16 v[94:97], v[182:185], v[222:225], v[94:97]
	v_mfma_f32_16x16x32_f16 v[82:85], v[152:155], v[230:233], v[82:85]
	v_mfma_f32_16x16x32_f16 v[78:81], v[182:185], v[230:233], v[78:81]
	v_mfma_f32_16x16x32_f16 v[130:133], v[178:181], v[210:213], v[130:133]
	v_mfma_f32_16x16x32_f16 v[126:129], v[186:189], v[210:213], v[126:129]
	v_mfma_f32_16x16x32_f16 v[114:117], v[178:181], v[218:221], v[114:117]
	v_mfma_f32_16x16x32_f16 v[110:113], v[186:189], v[218:221], v[110:113]
	v_mfma_f32_16x16x32_f16 v[98:101], v[178:181], v[226:229], v[98:101]
	v_mfma_f32_16x16x32_f16 v[94:97], v[186:189], v[226:229], v[94:97]
	v_mfma_f32_16x16x32_f16 v[82:85], v[178:181], v[234:237], v[82:85]
	v_mfma_f32_16x16x32_f16 v[78:81], v[186:189], v[234:237], v[78:81]
	v_mfma_f32_16x16x32_f16 v[122:125], v[190:193], v[206:209], v[122:125]
	v_mfma_f32_16x16x32_f16 v[118:121], v[198:201], v[206:209], v[118:121]
	v_mfma_f32_16x16x32_f16 v[106:109], v[190:193], v[214:217], v[106:109]
	v_mfma_f32_16x16x32_f16 v[102:105], v[198:201], v[214:217], v[102:105]
	v_mfma_f32_16x16x32_f16 v[90:93], v[190:193], v[222:225], v[90:93]
	v_mfma_f32_16x16x32_f16 v[86:89], v[198:201], v[222:225], v[86:89]
	v_mfma_f32_16x16x32_f16 v[74:77], v[190:193], v[230:233], v[74:77]
	v_mfma_f32_16x16x32_f16 v[70:73], v[198:201], v[230:233], v[70:73]
	v_mfma_f32_16x16x32_f16 v[122:125], v[194:197], v[210:213], v[122:125]
	v_mfma_f32_16x16x32_f16 v[118:121], v[202:205], v[210:213], v[118:121]
	v_mfma_f32_16x16x32_f16 v[106:109], v[194:197], v[218:221], v[106:109]
	v_mfma_f32_16x16x32_f16 v[102:105], v[202:205], v[218:221], v[102:105]
	v_mfma_f32_16x16x32_f16 v[90:93], v[194:197], v[226:229], v[90:93]
	v_mfma_f32_16x16x32_f16 v[86:89], v[202:205], v[226:229], v[86:89]
	v_mfma_f32_16x16x32_f16 v[74:77], v[194:197], v[234:237], v[74:77]
	v_mfma_f32_16x16x32_f16 v[70:73], v[202:205], v[234:237], v[70:73]
	s_barrier
; #define STAGE(bufoff, gbase, voff) do { _Pragma("unroll") for (int _i = 0; _i < 2; ++_i) \
;     __builtin_amdgcn_global_load_lds((const unsigned*)((const char*)(gbase) + (voff)[_i]), (LAS unsigned*)(lds + (bufoff) + ldsw + _i * 8192), 16, 0, 0); } while (0)
; #define LDA(dst, b, h) do { _Pragma("unroll") for (int m = 0; m < 4; ++m) _Pragma("unroll") for (int k = 0; k < 2; ++k) dst[m][k] = *(const LAS half8*)(lds + SA(b, h) + aoff + m * 2048 + k * 1024); } while (0)
; #define MMA(ai, bj, At_, Bt_) do { __builtin_amdgcn_s_setprio(1); \
;     _Pragma("unroll") for (int m = 0; m < 4; ++m) _Pragma("unroll") for (int n = 0; n < 2; ++n) _Pragma("unroll") for (int k = 0; k < 2; ++k) \
;       acc[ai][bj][m][n] = MFMA16(Bt_[n][k], At_[m][k], acc[ai][bj][m][n]); \
;     __builtin_amdgcn_s_setprio(0); } while (0)
; #define WAIT_V(n) asm volatile("s_waitcnt vmcnt(" #n ")" ::: "memory")
; #define WAIT_L(n) asm volatile("s_waitcnt lgkmcnt(" #n ")" ::: "memory")
; #define BAR __builtin_amdgcn_s_barrier()
; #define SCHED __builtin_amdgcn_sched_barrier(0)
; template <int EPI>
; DI void gemm_phase(const int wid_s, const h16* __restrict__ A, const h16* __restrict__ Bt, const int N, const int K, const EpiArgs ea) {
;     ...
;       LDA(At, 1, 1); STAGE(SB(1, 0), b3, voffB); STAGE(SB(1, 1), b3 + hstep, voffB); STAGE(SA(1, 0), a3, voffA);
;       WAIT_V(8); WAIT_L(0); BAR; MMA(1, 0, At, B0); MMA(1, 1, At, B1); BAR; SCHED;
;     }
	s_add_i32 s26, s49, s30
	v_lshl_add_u64 v[238:239], v[238:239], 0, s[36:37]
	s_mov_b32 m0, s26
	ds_read_b128 v[206:209], v151 offset:49152
	ds_read_b128 v[210:213], v151 offset:50176
	ds_read_b128 v[214:217], v151 offset:51200
	ds_read_b128 v[218:221], v151 offset:52224
	ds_read_b128 v[222:225], v151 offset:53248
	ds_read_b128 v[226:229], v151 offset:54272
	ds_read_b128 v[230:233], v151 offset:55296
	ds_read_b128 v[234:237], v151 offset:56320
	global_load_lds_dwordx4 v[238:239], off
	s_add_i32 m0, s26, 0x2000
	s_add_u32 s22, s22, 0x40080
	v_lshl_add_u64 v[238:239], v[240:241], 0, s[36:37]
	s_addc_u32 s23, s23, 0
	s_add_i32 s26, s50, s30
	global_load_lds_dwordx4 v[238:239], off
	v_lshl_add_u64 v[238:239], s[22:23], 0, v[0:1]
	s_mov_b32 m0, s26
	s_nop 0
	global_load_lds_dwordx4 v[238:239], off
	v_lshl_add_u64 v[238:239], s[22:23], 0, v[2:3]
	s_add_i32 m0, s26, 0x2000
	s_nop 0
	global_load_lds_dwordx4 v[238:239], off
	v_lshl_add_u64 v[238:239], v[242:243], 0, s[36:37]
	s_mov_b32 m0, s40
	s_nop 0
	global_load_lds_dwordx4 v[238:239], off
	v_lshl_add_u64 v[238:239], v[244:245], 0, s[36:37]
	s_mov_b32 m0, s41
	s_nop 0
	global_load_lds_dwordx4 v[238:239], off
	s_waitcnt vmcnt(8)
	s_waitcnt lgkmcnt(0)
	s_barrier
	s_waitcnt lgkmcnt(0)
	v_mfma_f32_16x16x32_f16 v[66:69], v[152:155], v[206:209], v[66:69]
	v_mfma_f32_16x16x32_f16 v[62:65], v[182:185], v[206:209], v[62:65]
	v_mfma_f32_16x16x32_f16 v[50:53], v[152:155], v[214:217], v[50:53]
	v_mfma_f32_16x16x32_f16 v[46:49], v[182:185], v[214:217], v[46:49]
	v_mfma_f32_16x16x32_f16 v[34:37], v[152:155], v[222:225], v[34:37]
	v_mfma_f32_16x16x32_f16 v[30:33], v[182:185], v[222:225], v[30:33]
	v_mfma_f32_16x16x32_f16 v[18:21], v[152:155], v[230:233], v[18:21]
	v_mfma_f32_16x16x32_f16 v[14:17], v[182:185], v[230:233], v[14:17]
	v_mfma_f32_16x16x32_f16 v[66:69], v[178:181], v[210:213], v[66:69]
	v_mfma_f32_16x16x32_f16 v[62:65], v[186:189], v[210:213], v[62:65]
	v_mfma_f32_16x16x32_f16 v[50:53], v[178:181], v[218:221], v[50:53]
	v_mfma_f32_16x16x32_f16 v[46:49], v[186:189], v[218:221], v[46:49]
	v_mfma_f32_16x16x32_f16 v[34:37], v[178:181], v[226:229], v[34:37]
	v_mfma_f32_16x16x32_f16 v[30:33], v[186:189], v[226:229], v[30:33]
	v_mfma_f32_16x16x32_f16 v[18:21], v[178:181], v[234:237], v[18:21]
	v_mfma_f32_16x16x32_f16 v[14:17], v[186:189], v[234:237], v[14:17]
	v_mfma_f32_16x16x32_f16 v[58:61], v[190:193], v[206:209], v[58:61]
	v_mfma_f32_16x16x32_f16 v[54:57], v[198:201], v[206:209], v[54:57]
	v_mfma_f32_16x16x32_f16 v[42:45], v[190:193], v[214:217], v[42:45]
	v_mfma_f32_16x16x32_f16 v[38:41], v[198:201], v[214:217], v[38:41]
	v_mfma_f32_16x16x32_f16 v[26:29], v[190:193], v[222:225], v[26:29]
	v_mfma_f32_16x16x32_f16 v[22:25], v[198:201], v[222:225], v[22:25]
	v_mfma_f32_16x16x32_f16 v[10:13], v[190:193], v[230:233], v[10:13]
	v_mfma_f32_16x16x32_f16 v[6:9], v[198:201], v[230:233], v[6:9]
	v_mfma_f32_16x16x32_f16 v[58:61], v[194:197], v[210:213], v[58:61]
	v_mfma_f32_16x16x32_f16 v[54:57], v[202:205], v[210:213], v[54:57]
	v_mfma_f32_16x16x32_f16 v[42:45], v[194:197], v[218:221], v[42:45]
	v_mfma_f32_16x16x32_f16 v[38:41], v[202:205], v[218:221], v[38:41]
	v_mfma_f32_16x16x32_f16 v[26:29], v[194:197], v[226:229], v[26:29]
	v_mfma_f32_16x16x32_f16 v[22:25], v[202:205], v[226:229], v[22:25]
	v_mfma_f32_16x16x32_f16 v[10:13], v[194:197], v[234:237], v[10:13]
	v_mfma_f32_16x16x32_f16 v[6:9], v[202:205], v[234:237], v[6:9]
	s_barrier
	s_add_i32 s48, s48, 2
	s_add_u32 s20, s20, 0x100
	s_addc_u32 s21, s21, 0
	s_cmp_gt_u32 s48, 13

; template <int EPI>
; DI void gemm_phase(const int wid_s, const h16* __restrict__ A, const h16* __restrict__ Bt, const int N, const int K, const EpiArgs ea) {
;     ...
;     for (int ai = 0; ai < 2; ++ai)
; #pragma unroll
;       for (int m = 0; m < 4; ++m) {
;         const size_t row = (size_t)(brow + ai * HALF + wr * 64 + m * 16 + fr);
; #pragma unroll
;         for (int bj = 0; bj < 2; ++bj) {
;           const int col0 = bcol + bj * HALF + wc * 32 + 8 * fq;
;           const f32x4 v0 = acc[ai][bj][m][0], v1 = acc[ai][bj][m][1];
;           if (EPI == 0) {
;             half8 o = {(h16)v0[0], (h16)v0[1], (h16)v0[2], (h16)v0[3], (h16)v1[0], (h16)v1[1], (h16)v1[2], (h16)v1[3]};
;             *(half8*)(ea.out + row * LDH + col0) = o;
;           } else if (EPI == 1) {
;             const half8 r = *(const half8*)(ea.res + row * 1024 + col0);
;             half8 o;
; #pragma unroll
;             for (int j = 0; j < 4; ++j) { o[j] = (h16)(ALPHA_F * (float)r[j] + v0[j]); o[4 + j] = (h16)(ALPHA_F * (float)r[4 + j] + v1[j]); }
;             *(half8*)(ea.out + row * 1024 + col0) = o;
;           } else {
;             const int f0 = (bcol + bj * HALF + wc * 32) / 2 + 4 * fq;
;             half4 o;
; #pragma unroll
;             for (int j = 0; j < 4; ++j) { const float g = v0[j], u = v1[j]; o[j] = (h16)(g * __builtin_amdgcn_rcpf(1.f + __builtin_amdgcn_exp2f(g * -1.4426950408889634f)) * u); }
;             *(half4*)(ea.out + row * DFF + f0) = o;
.LBB0_144:
	v_mul_f32_e32 v147, 0xbfb8aa3b, v130
	v_exp_f32_e32 v147, v147
	s_or_b32 s9, s18, s39
	s_ashr_i32 s9, s9, 1
	v_add_u32_e32 v146, s16, v5
	v_add_f32_e32 v147, 1.0, v147
	v_rcp_f32_e32 v154, v147
	v_mul_f32_e32 v147, 0xbfb8aa3b, v131
	v_exp_f32_e32 v147, v147
	v_mov_b64_e32 v[144:145], s[28:29]
	s_movk_i32 s11, 0x1600
	v_mad_i64_i32 v[152:153], s[20:21], v146, s11, v[144:145]
	v_add_f32_e32 v147, 1.0, v147
	v_rcp_f32_e32 v155, v147
	s_nop 0
	v_pk_mul_f32 v[130:131], v[130:131], v[154:155]
	s_nop 0
	v_pk_mul_f32 v[126:127], v[126:127], v[130:131]
	s_nop 0
	v_cvt_pk_f16_f32 v130, v126, v127
	v_mul_f32_e32 v126, 0xbfb8aa3b, v132
	v_mul_f32_e32 v127, 0xbfb8aa3b, v133
	v_exp_f32_e32 v126, v126
	v_exp_f32_e32 v127, v127
	v_add_f32_e32 v126, 1.0, v126
	v_add_f32_e32 v127, 1.0, v127
	v_rcp_f32_e32 v126, v126
	v_rcp_f32_e32 v127, v127
	s_nop 0
	v_pk_mul_f32 v[126:127], v[132:133], v[126:127]
	s_nop 0
	v_pk_mul_f32 v[126:127], v[128:129], v[126:127]
	s_nop 0
	v_cvt_pk_f16_f32 v131, v126, v127
	v_or_b32_e32 v126, s9, v150
	v_ashrrev_i32_e32 v127, 31, v126
	v_lshlrev_b64 v[126:127], 1, v[126:127]
	v_lshl_add_u64 v[128:129], v[152:153], 0, v[126:127]
	global_store_dwordx2 v[128:129], v[130:131], off
	v_mul_f32_e32 v130, 0xbfb8aa3b, v122
	v_mul_f32_e32 v131, 0xbfb8aa3b, v123
	v_exp_f32_e32 v130, v130
	v_exp_f32_e32 v131, v131
	v_add_f32_e32 v130, 1.0, v130
	v_add_f32_e32 v131, 1.0, v131
	v_rcp_f32_e32 v130, v130
	v_rcp_f32_e32 v131, v131
	s_nop 0
	v_pk_mul_f32 v[122:123], v[122:123], v[130:131]
	s_nop 0
	v_pk_mul_f32 v[118:119], v[118:119], v[122:123]
	s_nop 0
	v_cvt_pk_f16_f32 v118, v118, v119
	v_mul_f32_e32 v119, 0xbfb8aa3b, v124
	v_exp_f32_e32 v119, v119
	s_nop 0
	v_add_f32_e32 v119, 1.0, v119
	v_rcp_f32_e32 v122, v119
	v_mul_f32_e32 v119, 0xbfb8aa3b, v125
	v_exp_f32_e32 v119, v119
	s_nop 0
	v_add_f32_e32 v119, 1.0, v119
	v_rcp_f32_e32 v123, v119
	s_nop 0
	v_pk_mul_f32 v[122:123], v[124:125], v[122:123]
	s_nop 0
	v_pk_mul_f32 v[120:121], v[120:121], v[122:123]
	s_nop 0
	v_cvt_pk_f16_f32 v119, v120, v121
	global_store_dwordx2 v[128:129], v[118:119], off offset:128
	v_mul_f32_e32 v120, 0xbfb8aa3b, v114
	v_mul_f32_e32 v121, 0xbfb8aa3b, v115
	v_exp_f32_e32 v120, v120
	v_exp_f32_e32 v121, v121
	v_add_u32_e32 v118, 16, v146
	v_mad_i64_i32 v[118:119], s[20:21], v118, s11, v[144:145]
	v_add_f32_e32 v120, 1.0, v120
	v_add_f32_e32 v121, 1.0, v121
	v_rcp_f32_e32 v120, v120
	v_rcp_f32_e32 v121, v121
	s_nop 0
	v_pk_mul_f32 v[114:115], v[114:115], v[120:121]
	s_nop 0
	v_pk_mul_f32 v[110:111], v[110:111], v[114:115]
	s_nop 0
	v_cvt_pk_f16_f32 v110, v110, v111
	v_mul_f32_e32 v111, 0xbfb8aa3b, v116
	v_exp_f32_e32 v111, v111
	s_nop 0
	v_add_f32_e32 v111, 1.0, v111
	v_rcp_f32_e32 v114, v111
	v_mul_f32_e32 v111, 0xbfb8aa3b, v117
	v_exp_f32_e32 v111, v111
	s_nop 0
	v_add_f32_e32 v111, 1.0, v111
	v_rcp_f32_e32 v115, v111
	s_nop 0
	v_pk_mul_f32 v[114:115], v[116:117], v[114:115]
	s_nop 0
	v_pk_mul_f32 v[112:113], v[112:113], v[114:115]
	s_nop 0
	v_cvt_pk_f16_f32 v111, v112, v113
	v_lshl_add_u64 v[112:113], v[118:119], 0, v[126:127]
	global_store_dwordx2 v[112:113], v[110:111], off
	v_mul_f32_e32 v110, 0xbfb8aa3b, v106
	v_mul_f32_e32 v111, 0xbfb8aa3b, v107
	v_exp_f32_e32 v110, v110
	v_exp_f32_e32 v111, v111
	v_add_f32_e32 v110, 1.0, v110
	v_add_f32_e32 v111, 1.0, v111
	v_rcp_f32_e32 v110, v110
	v_rcp_f32_e32 v111, v111
	s_nop 0
	v_pk_mul_f32 v[106:107], v[106:107], v[110:111]
	s_nop 0
	v_pk_mul_f32 v[102:103], v[102:103], v[106:107]
	s_nop 0
	v_cvt_pk_f16_f32 v102, v102, v103
	v_mul_f32_e32 v103, 0xbfb8aa3b, v108
	v_exp_f32_e32 v103, v103
	s_nop 0
	v_add_f32_e32 v103, 1.0, v103
	v_rcp_f32_e32 v106, v103
	v_mul_f32_e32 v103, 0xbfb8aa3b, v109
	v_exp_f32_e32 v103, v103
	s_nop 0
	v_add_f32_e32 v103, 1.0, v103
	v_rcp_f32_e32 v107, v103
	s_nop 0
	v_pk_mul_f32 v[106:107], v[108:109], v[106:107]
	s_nop 0
	v_pk_mul_f32 v[104:105], v[104:105], v[106:107]
	s_nop 0
	v_cvt_pk_f16_f32 v103, v104, v105
	global_store_dwordx2 v[112:113], v[102:103], off offset:128
	v_mul_f32_e32 v104, 0xbfb8aa3b, v98
	v_mul_f32_e32 v105, 0xbfb8aa3b, v99
	v_exp_f32_e32 v104, v104
	v_exp_f32_e32 v105, v105
	v_add_u32_e32 v102, 32, v146
	v_mad_i64_i32 v[102:103], s[20:21], v102, s11, v[144:145]
	v_add_f32_e32 v104, 1.0, v104
	v_add_f32_e32 v105, 1.0, v105
	v_rcp_f32_e32 v104, v104
	v_rcp_f32_e32 v105, v105
	s_nop 0
	v_pk_mul_f32 v[98:99], v[98:99], v[104:105]
	s_nop 0
	v_pk_mul_f32 v[94:95], v[94:95], v[98:99]
	s_nop 0
	v_cvt_pk_f16_f32 v94, v94, v95
	v_mul_f32_e32 v95, 0xbfb8aa3b, v100
	v_exp_f32_e32 v95, v95
	s_nop 0
	v_add_f32_e32 v95, 1.0, v95
	v_rcp_f32_e32 v98, v95
	v_mul_f32_e32 v95, 0xbfb8aa3b, v101
	v_exp_f32_e32 v95, v95
	s_nop 0
	v_add_f32_e32 v95, 1.0, v95
	v_rcp_f32_e32 v99, v95
	s_nop 0
	v_pk_mul_f32 v[98:99], v[100:101], v[98:99]
	s_nop 0
	v_pk_mul_f32 v[96:97], v[96:97], v[98:99]
	s_nop 0
	v_cvt_pk_f16_f32 v95, v96, v97
	v_lshl_add_u64 v[96:97], v[102:103], 0, v[126:127]
	global_store_dwordx2 v[96:97], v[94:95], off
	v_mul_f32_e32 v94, 0xbfb8aa3b, v90
	v_mul_f32_e32 v95, 0xbfb8aa3b, v91
	v_exp_f32_e32 v94, v94
	v_exp_f32_e32 v95, v95
	v_add_f32_e32 v94, 1.0, v94
	v_add_f32_e32 v95, 1.0, v95
	v_rcp_f32_e32 v94, v94
	v_rcp_f32_e32 v95, v95
	s_nop 0
	v_pk_mul_f32 v[90:91], v[90:91], v[94:95]
	s_nop 0
	v_pk_mul_f32 v[86:87], v[86:87], v[90:91]
	s_nop 0
	v_cvt_pk_f16_f32 v86, v86, v87
	v_mul_f32_e32 v87, 0xbfb8aa3b, v92
	v_exp_f32_e32 v87, v87
	s_nop 0
	v_add_f32_e32 v87, 1.0, v87
	v_rcp_f32_e32 v90, v87
	v_mul_f32_e32 v87, 0xbfb8aa3b, v93
	v_exp_f32_e32 v87, v87
	s_nop 0
	v_add_f32_e32 v87, 1.0, v87
	v_rcp_f32_e32 v91, v87
	s_nop 0
	v_pk_mul_f32 v[90:91], v[92:93], v[90:91]
	s_nop 0
; template <int EPI>
; DI void gemm_phase(const int wid_s, const h16* __restrict__ A, const h16* __restrict__ Bt, const int N, const int K, const EpiArgs ea) {
;     ...
;             const int f0 = (bcol + bj * HALF + wc * 32) / 2 + 4 * fq;
;             half4 o;
; #pragma unroll
;             for (int j = 0; j < 4; ++j) { const float g = v0[j], u = v1[j]; o[j] = (h16)(g * __builtin_amdgcn_rcpf(1.f + __builtin_amdgcn_exp2f(g * -1.4426950408889634f)) * u); }
;             *(half4*)(ea.out + row * DFF + f0) = o;
	v_pk_mul_f32 v[88:89], v[88:89], v[90:91]
	s_nop 0
	v_cvt_pk_f16_f32 v87, v88, v89
	global_store_dwordx2 v[96:97], v[86:87], off offset:128
	v_mul_f32_e32 v88, 0xbfb8aa3b, v82
	v_mul_f32_e32 v89, 0xbfb8aa3b, v83
	v_exp_f32_e32 v88, v88
	v_exp_f32_e32 v89, v89
	v_add_u32_e32 v86, 48, v146
	v_mad_i64_i32 v[86:87], s[20:21], v86, s11, v[144:145]
	v_add_f32_e32 v88, 1.0, v88
	v_add_f32_e32 v89, 1.0, v89
	v_rcp_f32_e32 v88, v88
	v_rcp_f32_e32 v89, v89
	s_nop 0
	v_pk_mul_f32 v[82:83], v[82:83], v[88:89]
	s_nop 0
	v_pk_mul_f32 v[78:79], v[78:79], v[82:83]
	s_nop 0
	v_cvt_pk_f16_f32 v78, v78, v79
	v_mul_f32_e32 v79, 0xbfb8aa3b, v84
	v_exp_f32_e32 v79, v79
	s_nop 0
	v_add_f32_e32 v79, 1.0, v79
	v_rcp_f32_e32 v82, v79
	v_mul_f32_e32 v79, 0xbfb8aa3b, v85
	v_exp_f32_e32 v79, v79
	s_nop 0
	v_add_f32_e32 v79, 1.0, v79
	v_rcp_f32_e32 v83, v79
	s_nop 0
	v_pk_mul_f32 v[82:83], v[84:85], v[82:83]
	s_nop 0
	v_pk_mul_f32 v[80:81], v[80:81], v[82:83]
	s_nop 0
	v_cvt_pk_f16_f32 v79, v80, v81
	v_lshl_add_u64 v[80:81], v[86:87], 0, v[126:127]
	global_store_dwordx2 v[80:81], v[78:79], off
	v_mul_f32_e32 v78, 0xbfb8aa3b, v74
	v_mul_f32_e32 v79, 0xbfb8aa3b, v75
	v_exp_f32_e32 v78, v78
	v_exp_f32_e32 v79, v79
	v_add_f32_e32 v78, 1.0, v78
	v_add_f32_e32 v79, 1.0, v79
	v_rcp_f32_e32 v78, v78
	v_rcp_f32_e32 v79, v79
	s_nop 0
	v_pk_mul_f32 v[74:75], v[74:75], v[78:79]
	s_nop 0
	v_pk_mul_f32 v[70:71], v[70:71], v[74:75]
	s_nop 0
	v_cvt_pk_f16_f32 v70, v70, v71
	v_mul_f32_e32 v71, 0xbfb8aa3b, v76
	v_exp_f32_e32 v71, v71
	s_nop 0
	v_add_f32_e32 v71, 1.0, v71
	v_rcp_f32_e32 v74, v71
	v_mul_f32_e32 v71, 0xbfb8aa3b, v77
	v_exp_f32_e32 v71, v71
	s_nop 0
	v_add_f32_e32 v71, 1.0, v71
	v_rcp_f32_e32 v75, v71
	s_nop 0
	v_pk_mul_f32 v[74:75], v[76:77], v[74:75]
	s_nop 0
	v_pk_mul_f32 v[72:73], v[72:73], v[74:75]
	s_nop 0
	v_cvt_pk_f16_f32 v71, v72, v73
	global_store_dwordx2 v[80:81], v[70:71], off offset:128
	v_mul_f32_e32 v72, 0xbfb8aa3b, v66
	v_mul_f32_e32 v73, 0xbfb8aa3b, v67
	v_exp_f32_e32 v72, v72
	v_exp_f32_e32 v73, v73
	v_add_u32_e32 v70, 0x80, v146
	v_mad_i64_i32 v[70:71], s[20:21], v70, s11, v[144:145]
	v_add_f32_e32 v72, 1.0, v72
	v_add_f32_e32 v73, 1.0, v73
	v_rcp_f32_e32 v72, v72
	v_rcp_f32_e32 v73, v73
	s_nop 0
	v_pk_mul_f32 v[66:67], v[66:67], v[72:73]
	s_nop 0
	v_pk_mul_f32 v[62:63], v[62:63], v[66:67]
	s_nop 0
	v_cvt_pk_f16_f32 v62, v62, v63
	v_mul_f32_e32 v63, 0xbfb8aa3b, v68
	v_exp_f32_e32 v63, v63
	s_nop 0
	v_add_f32_e32 v63, 1.0, v63
	v_rcp_f32_e32 v66, v63
	v_mul_f32_e32 v63, 0xbfb8aa3b, v69
	v_exp_f32_e32 v63, v63
	s_nop 0
	v_add_f32_e32 v63, 1.0, v63
	v_rcp_f32_e32 v67, v63
	s_nop 0
	v_pk_mul_f32 v[66:67], v[68:69], v[66:67]
	s_nop 0
	v_pk_mul_f32 v[64:65], v[64:65], v[66:67]
	s_nop 0
	v_cvt_pk_f16_f32 v63, v64, v65
	v_lshl_add_u64 v[64:65], v[70:71], 0, v[126:127]
	global_store_dwordx2 v[64:65], v[62:63], off
	v_mul_f32_e32 v62, 0xbfb8aa3b, v58
	v_mul_f32_e32 v63, 0xbfb8aa3b, v59
	v_exp_f32_e32 v62, v62
	v_exp_f32_e32 v63, v63
	v_add_f32_e32 v62, 1.0, v62
	v_add_f32_e32 v63, 1.0, v63
	v_rcp_f32_e32 v62, v62
	v_rcp_f32_e32 v63, v63
	s_nop 0
	v_pk_mul_f32 v[58:59], v[58:59], v[62:63]
	s_nop 0
	v_pk_mul_f32 v[54:55], v[54:55], v[58:59]
	s_nop 0
	v_cvt_pk_f16_f32 v54, v54, v55
	v_mul_f32_e32 v55, 0xbfb8aa3b, v60
	v_exp_f32_e32 v55, v55
	s_nop 0
	v_add_f32_e32 v55, 1.0, v55
	v_rcp_f32_e32 v58, v55
	v_mul_f32_e32 v55, 0xbfb8aa3b, v61
	v_exp_f32_e32 v55, v55
	s_nop 0
	v_add_f32_e32 v55, 1.0, v55
	v_rcp_f32_e32 v59, v55
	s_nop 0
	v_pk_mul_f32 v[58:59], v[60:61], v[58:59]
	s_nop 0
	v_pk_mul_f32 v[56:57], v[56:57], v[58:59]
	s_nop 0
	v_cvt_pk_f16_f32 v55, v56, v57
	global_store_dwordx2 v[64:65], v[54:55], off offset:128
	v_mul_f32_e32 v56, 0xbfb8aa3b, v50
	v_mul_f32_e32 v57, 0xbfb8aa3b, v51
	v_exp_f32_e32 v56, v56
	v_exp_f32_e32 v57, v57
	v_add_u32_e32 v54, 0x90, v146
	v_mad_i64_i32 v[54:55], s[20:21], v54, s11, v[144:145]
	v_add_f32_e32 v56, 1.0, v56
	v_add_f32_e32 v57, 1.0, v57
	v_rcp_f32_e32 v56, v56
	v_rcp_f32_e32 v57, v57
	s_nop 0
	v_pk_mul_f32 v[50:51], v[50:51], v[56:57]
	s_nop 0
	v_pk_mul_f32 v[46:47], v[46:47], v[50:51]
	s_nop 0
	v_cvt_pk_f16_f32 v46, v46, v47
	v_mul_f32_e32 v47, 0xbfb8aa3b, v52
	v_exp_f32_e32 v47, v47
	s_nop 0
	v_add_f32_e32 v47, 1.0, v47
	v_rcp_f32_e32 v50, v47
	v_mul_f32_e32 v47, 0xbfb8aa3b, v53
	v_exp_f32_e32 v47, v47
	s_nop 0
	v_add_f32_e32 v47, 1.0, v47
	v_rcp_f32_e32 v51, v47
	s_nop 0
	v_pk_mul_f32 v[50:51], v[52:53], v[50:51]
	s_nop 0
	v_pk_mul_f32 v[48:49], v[48:49], v[50:51]
	s_nop 0
	v_cvt_pk_f16_f32 v47, v48, v49
	v_lshl_add_u64 v[48:49], v[54:55], 0, v[126:127]
	global_store_dwordx2 v[48:49], v[46:47], off
; #define BAR __builtin_amdgcn_s_barrier()
; template <int EPI>
; DI void gemm_phase(const int wid_s, const h16* __restrict__ A, const h16* __restrict__ Bt, const int N, const int K, const EpiArgs ea) {
;     ...
;             const int f0 = (bcol + bj * HALF + wc * 32) / 2 + 4 * fq;
;             half4 o;
; #pragma unroll
;             for (int j = 0; j < 4; ++j) { const float g = v0[j], u = v1[j]; o[j] = (h16)(g * __builtin_amdgcn_rcpf(1.f + __builtin_amdgcn_exp2f(g * -1.4426950408889634f)) * u); }
;             *(half4*)(ea.out + row * DFF + f0) = o;
;     ...
;     if (!has_next) break;
; #pragma unroll
;     for (int a = 0; a < 2; ++a)
; #pragma unroll
;       for (int b = 0; b < 2; ++b)
; #pragma unroll
;         for (int m = 0; m < 4; ++m)
; #pragma unroll
;           for (int n = 0; n < 2; ++n) acc[a][b][m][n] = (f32x4){0.f, 0.f, 0.f, 0.f};
;     L = Ln; brow = nbrow; bcol = nbcol; cA = nA; cB = nB;
;     if (wr == 1) BAR;
	v_mul_f32_e32 v46, 0xbfb8aa3b, v42
	v_mul_f32_e32 v47, 0xbfb8aa3b, v43
	v_exp_f32_e32 v46, v46
	v_exp_f32_e32 v47, v47
	v_add_f32_e32 v46, 1.0, v46
	v_add_f32_e32 v47, 1.0, v47
	v_rcp_f32_e32 v46, v46
	v_rcp_f32_e32 v47, v47
	s_nop 0
	v_pk_mul_f32 v[42:43], v[42:43], v[46:47]
	s_nop 0
	v_pk_mul_f32 v[38:39], v[38:39], v[42:43]
	s_nop 0
	v_cvt_pk_f16_f32 v38, v38, v39
	v_mul_f32_e32 v39, 0xbfb8aa3b, v44
	v_exp_f32_e32 v39, v39
	s_nop 0
	v_add_f32_e32 v39, 1.0, v39
	v_rcp_f32_e32 v42, v39
	v_mul_f32_e32 v39, 0xbfb8aa3b, v45
	v_exp_f32_e32 v39, v39
	s_nop 0
	v_add_f32_e32 v39, 1.0, v39
	v_rcp_f32_e32 v43, v39
	s_nop 0
	v_pk_mul_f32 v[42:43], v[44:45], v[42:43]
	s_nop 0
	v_pk_mul_f32 v[40:41], v[40:41], v[42:43]
	s_nop 0
	v_cvt_pk_f16_f32 v39, v40, v41
	global_store_dwordx2 v[48:49], v[38:39], off offset:128
	v_mul_f32_e32 v40, 0xbfb8aa3b, v34
	v_mul_f32_e32 v41, 0xbfb8aa3b, v35
	v_exp_f32_e32 v40, v40
	v_exp_f32_e32 v41, v41
	v_add_u32_e32 v38, 0xa0, v146
	v_mad_i64_i32 v[38:39], s[20:21], v38, s11, v[144:145]
	v_add_f32_e32 v40, 1.0, v40
	v_add_f32_e32 v41, 1.0, v41
	v_rcp_f32_e32 v40, v40
	v_rcp_f32_e32 v41, v41
	s_nop 0
	v_pk_mul_f32 v[34:35], v[34:35], v[40:41]
	s_nop 0
	v_pk_mul_f32 v[30:31], v[30:31], v[34:35]
	s_nop 0
	v_cvt_pk_f16_f32 v30, v30, v31
	v_mul_f32_e32 v31, 0xbfb8aa3b, v36
	v_exp_f32_e32 v31, v31
	s_nop 0
	v_add_f32_e32 v31, 1.0, v31
	v_rcp_f32_e32 v34, v31
	v_mul_f32_e32 v31, 0xbfb8aa3b, v37
	v_exp_f32_e32 v31, v31
	s_nop 0
	v_add_f32_e32 v31, 1.0, v31
	v_rcp_f32_e32 v35, v31
	s_nop 0
	v_pk_mul_f32 v[34:35], v[36:37], v[34:35]
	s_nop 0
	v_pk_mul_f32 v[32:33], v[32:33], v[34:35]
	s_nop 0
	v_cvt_pk_f16_f32 v31, v32, v33
	v_lshl_add_u64 v[32:33], v[38:39], 0, v[126:127]
	global_store_dwordx2 v[32:33], v[30:31], off
	v_mul_f32_e32 v30, 0xbfb8aa3b, v26
	v_mul_f32_e32 v31, 0xbfb8aa3b, v27
	v_exp_f32_e32 v30, v30
	v_exp_f32_e32 v31, v31
	v_add_f32_e32 v30, 1.0, v30
	v_add_f32_e32 v31, 1.0, v31
	v_rcp_f32_e32 v30, v30
	v_rcp_f32_e32 v31, v31
	s_nop 0
	v_pk_mul_f32 v[26:27], v[26:27], v[30:31]
	s_nop 0
	v_pk_mul_f32 v[22:23], v[22:23], v[26:27]
	s_nop 0
	v_cvt_pk_f16_f32 v22, v22, v23
	v_mul_f32_e32 v23, 0xbfb8aa3b, v28
	v_exp_f32_e32 v23, v23
	s_nop 0
	v_add_f32_e32 v23, 1.0, v23
	v_rcp_f32_e32 v26, v23
	v_mul_f32_e32 v23, 0xbfb8aa3b, v29
	v_exp_f32_e32 v23, v23
	s_nop 0
	v_add_f32_e32 v23, 1.0, v23
	v_rcp_f32_e32 v27, v23
	s_nop 0
	v_pk_mul_f32 v[26:27], v[28:29], v[26:27]
	s_nop 0
	v_pk_mul_f32 v[24:25], v[24:25], v[26:27]
	s_nop 0
	v_cvt_pk_f16_f32 v23, v24, v25
	global_store_dwordx2 v[32:33], v[22:23], off offset:128
	v_mul_f32_e32 v24, 0xbfb8aa3b, v18
	v_mul_f32_e32 v25, 0xbfb8aa3b, v19
	v_exp_f32_e32 v24, v24
	v_exp_f32_e32 v25, v25
	v_add_u32_e32 v22, 0xb0, v146
	v_mad_i64_i32 v[22:23], s[20:21], v22, s11, v[144:145]
	v_add_f32_e32 v24, 1.0, v24
	v_add_f32_e32 v25, 1.0, v25
	v_rcp_f32_e32 v24, v24
	v_rcp_f32_e32 v25, v25
	s_nop 0
	v_pk_mul_f32 v[18:19], v[18:19], v[24:25]
	s_nop 0
	v_pk_mul_f32 v[14:15], v[14:15], v[18:19]
	s_nop 0
	v_cvt_pk_f16_f32 v14, v14, v15
	v_mul_f32_e32 v15, 0xbfb8aa3b, v20
	v_exp_f32_e32 v15, v15
	s_nop 0
	v_add_f32_e32 v15, 1.0, v15
	v_rcp_f32_e32 v18, v15
	v_mul_f32_e32 v15, 0xbfb8aa3b, v21
	v_exp_f32_e32 v15, v15
	s_nop 0
	v_add_f32_e32 v15, 1.0, v15
	v_rcp_f32_e32 v19, v15
	s_nop 0
	v_pk_mul_f32 v[18:19], v[20:21], v[18:19]
	s_nop 0
	v_pk_mul_f32 v[16:17], v[16:17], v[18:19]
	s_nop 0
	v_cvt_pk_f16_f32 v15, v16, v17
	v_lshl_add_u64 v[16:17], v[22:23], 0, v[126:127]
	global_store_dwordx2 v[16:17], v[14:15], off
	v_mul_f32_e32 v14, 0xbfb8aa3b, v10
	v_mul_f32_e32 v15, 0xbfb8aa3b, v11
	v_exp_f32_e32 v14, v14
	v_exp_f32_e32 v15, v15
	v_add_f32_e32 v14, 1.0, v14
	v_add_f32_e32 v15, 1.0, v15
	v_rcp_f32_e32 v14, v14
	v_rcp_f32_e32 v15, v15
	s_nop 0
	v_pk_mul_f32 v[10:11], v[10:11], v[14:15]
	s_nop 0
	v_pk_mul_f32 v[6:7], v[6:7], v[10:11]
	s_nop 0
	v_cvt_pk_f16_f32 v6, v6, v7
	v_mul_f32_e32 v7, 0xbfb8aa3b, v12
	v_exp_f32_e32 v7, v7
	s_nop 0
	v_add_f32_e32 v7, 1.0, v7
	v_rcp_f32_e32 v10, v7
	v_mul_f32_e32 v7, 0xbfb8aa3b, v13
	v_exp_f32_e32 v7, v7
	s_nop 0
	v_add_f32_e32 v7, 1.0, v7
	v_rcp_f32_e32 v11, v7
	s_nop 0
	v_pk_mul_f32 v[10:11], v[12:13], v[10:11]
	s_nop 0
	v_pk_mul_f32 v[8:9], v[8:9], v[10:11]
	s_nop 0
	v_cvt_pk_f16_f32 v7, v8, v9
	global_store_dwordx2 v[16:17], v[6:7], off offset:128
	v_readlane_b32 s48, v249, 37
	v_readlane_b32 s50, v249, 41
	s_andn2_b64 vcc, exec, s[6:7]
	s_mov_b64 s[6:7], -1
	s_movk_i32 s26, 0x1fff
	v_readlane_b32 s49, v249, 38
	v_readlane_b32 s51, v249, 42
	s_cbranch_vccnz .LBB0_137
	s_andn2_b64 vcc, exec, s[0:1]
	s_cbranch_vccnz .LBB0_136
	s_barrier
	s_branch .LBB0_136

; __device__ __forceinline__ int opaque_tid(int wid_s) { int t = wid_s * 64 + lane_id_hw(); asm volatile("" : "+v"(t)); return t; }
; #define STAGE(bufoff, gbase, voff) do { _Pragma("unroll") for (int _i = 0; _i < 2; ++_i) \
;     __builtin_amdgcn_global_load_lds((const unsigned*)((const char*)(gbase) + (voff)[_i]), (LAS unsigned*)(lds + (bufoff) + ldsw + _i * 8192), 16, 0, 0); } while (0)
; #define WAIT_V(n) asm volatile("s_waitcnt vmcnt(" #n ")" ::: "memory")
; #define BAR __builtin_amdgcn_s_barrier()
; template <int EPI>
; DI void gemm_phase(const int wid_s, const h16* __restrict__ A, const h16* __restrict__ Bt, const int N, const int K, const EpiArgs ea) {
;     ...
;   const int tid = opaque_tid(wid_s), wid = __builtin_amdgcn_readfirstlane(tid >> 6), lane = tid & 63, wr = wid >> 2, wc = wid & 3, fr = lane & 15, fq = lane >> 4;
;   unsigned voffA[2], voffB[2];
; #pragma unroll
;   for (int i = 0; i < 2; ++i) { int R, C; stage_rc(tid * 16 + i * 8192, R, C); const int Rb = (R & ~31) + perm32(R & 31);
;     voffA[i] = (unsigned)(R * K + C) * 2u; voffB[i] = (unsigned)(Rb * K + C) * 2u; }
;   const size_t kstep = (size_t)(BK * 2), hstep = (size_t)HALF * K * 2;
;   const unsigned ldsw = (unsigned)wid * 1024u;
;   const int aoff = lds_byte(wr * 64 + fr, fq * 8), boff = lds_byte(wc * 32 + fr, fq * 8);
;     ...
;   STAGE(SB(0, 0), cB, voffB); STAGE(SB(0, 1), cB + hstep, voffB); STAGE(SA(0, 0), cA, voffA); STAGE(SA(0, 1), cA + hstep, voffA);
;   if (wr == 1) BAR;
;   WAIT_V(2); BAR;
;   STAGE(SB(1, 0), cB + kstep, voffB); STAGE(SA(1, 0), cA + kstep, voffA); STAGE(SB(1, 1), cB + hstep + kstep, voffB);
;   WAIT_V(6); BAR;
.LBB0_165:
	v_lshrrev_b32_e32 v22, 1, v11
	v_and_b32_e32 v22, 24, v22
	v_and_b32_e32 v13, 15, v11
	v_lshlrev_b32_e32 v23, 1, v22
	v_lshlrev_b32_e32 v11, 2, v11
	v_lshl_or_b32 v5, s7, 6, v13
	v_lshl_or_b32 v13, v13, 6, v23
	s_lshl_b32 s7, s7, 13
	v_and_b32_e32 v11, 32, v11
	v_lshl_add_u64 v[14:15], s[4:5], 0, v[0:1]
	v_mov_b32_e32 v139, v1
	v_bitop3_b32 v23, v13, s7, v11 bitop3:0xde
	s_lshl_b32 s7, s8, 5
	v_lshl_add_u64 v[16:17], s[4:5], 0, v[138:139]
	v_mov_b32_e32 v3, v1
	s_and_b32 s7, s7, 0x60
	s_add_i32 m0, s17, 0x18000
	v_lshl_add_u64 v[14:15], v[14:15], 0, s[36:37]
	v_lshl_add_u64 v[18:19], s[22:23], 0, v[2:3]
	v_mov_b32_e32 v135, v1
	s_lshl_b32 s8, s7, 7
	s_waitcnt vmcnt(2)
	s_barrier
	global_load_lds_dwordx4 v[14:15], off
	v_lshl_add_u64 v[14:15], v[16:17], 0, s[36:37]
	s_add_i32 m0, s17, 0x1a000
	s_add_i32 s39, s17, 0x8000
	s_add_i32 s40, s17, 0xa000
	v_lshl_add_u64 v[20:21], s[22:23], 0, v[134:135]
	global_load_lds_dwordx4 v[14:15], off
	v_lshl_add_u64 v[14:15], v[18:19], 0, s[36:37]
	s_mov_b32 m0, s39
	s_add_u32 s4, s4, 0x40080
	global_load_lds_dwordx4 v[14:15], off
	v_lshl_add_u64 v[14:15], v[20:21], 0, s[36:37]
	s_mov_b32 m0, s40
	s_addc_u32 s5, s5, 0
	global_load_lds_dwordx4 v[14:15], off
	s_add_i32 m0, s17, 0x1c000
	v_lshl_add_u64 v[14:15], s[4:5], 0, v[0:1]
	global_load_lds_dwordx4 v[14:15], off
	v_lshl_add_u64 v[14:15], s[4:5], 0, v[138:139]
	s_add_i32 m0, s17, 0x1e000
	v_bitop3_b32 v148, v13, s8, v11 bitop3:0xde
	global_load_lds_dwordx4 v[14:15], off
	v_lshlrev_b32_e32 v11, 14, v9
	v_and_b32_e32 v11, 0xffff8000, v11
	v_lshl_add_u32 v10, v10, 11, v11
	v_and_b32_e32 v9, 1, v9
	v_lshl_or_b32 v9, v9, 6, v10
	v_lshl_add_u32 v140, v12, 1, v9
	v_lshlrev_b32_e32 v9, 14, v6
	v_and_b32_e32 v9, 0xffff8000, v9
	s_waitcnt vmcnt(0)
	v_lshl_add_u32 v7, v7, 11, v9
	v_and_b32_e32 v6, 1, v6
	s_cmpk_lt_u32 s6, 0x100
	v_lshl_or_b32 v6, v6, 6, v7
	s_cselect_b64 s[4:5], -1, 0
	v_or_b32_e32 v150, s7, v22
	v_mov_b32_e32 v141, v1
	v_lshl_add_u32 v142, v8, 1, v6
	v_mov_b32_e32 v143, v1
	v_add_u32_e32 v151, 0, v23
	s_barrier
	s_branch .LBB0_168

; #define STAGE(bufoff, gbase, voff) do { _Pragma("unroll") for (int _i = 0; _i < 2; ++_i) \
;     __builtin_amdgcn_global_load_lds((const unsigned*)((const char*)(gbase) + (voff)[_i]), (LAS unsigned*)(lds + (bufoff) + ldsw + _i * 8192), 16, 0, 0); } while (0)
; #define LDA(dst, b, h) do { _Pragma("unroll") for (int m = 0; m < 4; ++m) _Pragma("unroll") for (int k = 0; k < 2; ++k) dst[m][k] = *(const LAS half8*)(lds + SA(b, h) + aoff + m * 2048 + k * 1024); } while (0)
; #define LDB(dst, b, h) do { _Pragma("unroll") for (int n = 0; n < 2; ++n) _Pragma("unroll") for (int k = 0; k < 2; ++k) dst[n][k] = *(const LAS half8*)(lds + SB(b, h) + boff + n * 2048 + k * 1024); } while (0)
; #define MMA(ai, bj, At_, Bt_) do { __builtin_amdgcn_s_setprio(1); \
;     _Pragma("unroll") for (int m = 0; m < 4; ++m) _Pragma("unroll") for (int n = 0; n < 2; ++n) _Pragma("unroll") for (int k = 0; k < 2; ++k) \
;       acc[ai][bj][m][n] = MFMA16(Bt_[n][k], At_[m][k], acc[ai][bj][m][n]); \
;     __builtin_amdgcn_s_setprio(0); } while (0)
; #define WAIT_V(n) asm volatile("s_waitcnt vmcnt(" #n ")" ::: "memory")
; #define WAIT_L(n) asm volatile("s_waitcnt lgkmcnt(" #n ")" ::: "memory")
; #define BAR __builtin_amdgcn_s_barrier()
; template <int EPI>
; DI void gemm_phase(const int wid_s, const h16* __restrict__ A, const h16* __restrict__ Bt, const int N, const int K, const EpiArgs ea) {
;     ...
;     const int Ln = L + (int)gridDim.x;
;     const bool has_next = Ln < nwg;
;     int nbrow = brow, nbcol = bcol;
;     if (has_next) TILE_RC(Ln, nbrow, nbcol);
;     const char* nA = (const char*)A + (size_t)nbrow * K * 2;
;     const char* nB = (const char*)Bt + (size_t)nbcol * K * 2;
;     for (int t = 0; t < nt; t += 2) {
;       const bool last = (t == nt - 2);
;       const char* a1 = cA + (size_t)(t + 1) * kstep;
;       const char* a2 = last ? nA : cA + (size_t)(t + 2) * kstep; const char* b2 = last ? nB : cB + (size_t)(t + 2) * kstep;
;       const char* a3 = a2 + kstep; const char* b3 = b2 + kstep;
;       LDB(B0, 0, 0); LDB(B1, 0, 1); SCHED; LDA(At, 0, 0); STAGE(SA(1, 1), a1 + hstep, voffA);
;       WAIT_V(8); WAIT_L(0); BAR; MMA(0, 0, At, B0); MMA(0, 1, At, B1); BAR; SCHED;
;       LDA(At, 0, 1); STAGE(SB(0, 0), b2, voffB); STAGE(SB(0, 1), b2 + hstep, voffB); STAGE(SA(0, 0), a2, voffA);
;       WAIT_V(8); WAIT_L(0); BAR; MMA(1, 0, At, B0); MMA(1, 1, At, B1); BAR; SCHED;
.LBB0_174:
	s_ashr_i32 s9, s8, 31
	s_lshl_b64 s[12:13], s[8:9], 11
	v_readlane_b32 s14, v250, 46
	v_readlane_b32 s15, v250, 47
	s_add_u32 s12, s14, s12
	s_addc_u32 s13, s15, s13
	s_ashr_i32 s11, s10, 31
	s_lshl_b64 s[14:15], s[10:11], 11
	v_readlane_b32 s9, v249, 6
	s_add_u32 s9, s9, s14
	v_readlane_b32 s11, v249, 7
	s_addc_u32 s11, s11, s15
	v_readlane_b32 s26, v249, 27
	s_add_u32 s41, s26, s20
	v_readlane_b32 s20, v249, 28
	s_addc_u32 s42, s20, s21
	s_add_u32 s20, s22, 0x40080
	v_mov_b32_e32 v6, 0
	s_addc_u32 s21, s23, 0
	s_mov_b32 s43, -2
	s_add_u32 s22, s20, 0xfffc0080
	s_addc_u32 s23, s21, -1
	s_add_i32 s44, 0, 0x10000
	s_cmp_eq_u32 s43, 12
	s_cselect_b32 s27, s13, s23
	s_cselect_b32 s26, s12, s22
	v_add_u32_e32 v177, s44, v148
	s_cselect_b32 s23, s11, s42
	s_cselect_b32 s22, s9, s41
	s_add_i32 s46, 0, 0x14000
	ds_read_b128 v[144:147], v177
	ds_read_b128 v[152:155], v177 offset:1024
	ds_read_b128 v[178:181], v177 offset:2048
	ds_read_b128 v[182:185], v177 offset:3072
	v_add_u32_e32 v177, s46, v148
	ds_read_b128 v[186:189], v177
	ds_read_b128 v[190:193], v177 offset:1024
	ds_read_b128 v[194:197], v177 offset:2048
	ds_read_b128 v[198:201], v177 offset:3072
	v_lshl_add_u64 v[234:235], s[20:21], 0, v[142:143]
	s_add_i32 m0, s17, 0xc000
	ds_read_b128 v[202:205], v151
	ds_read_b128 v[206:209], v151 offset:1024
	ds_read_b128 v[210:213], v151 offset:2048
	ds_read_b128 v[214:217], v151 offset:3072
	ds_read_b128 v[218:221], v151 offset:4096
	ds_read_b128 v[222:225], v151 offset:5120
	ds_read_b128 v[226:229], v151 offset:6144
	ds_read_b128 v[230:233], v151 offset:7168
	global_load_lds_dwordx4 v[234:235], off
	v_lshl_add_u64 v[234:235], s[20:21], 0, v[140:141]
	s_add_i32 m0, s17, 0xe000
	s_nop 0
	global_load_lds_dwordx4 v[234:235], off
	s_waitcnt vmcnt(24)
	s_waitcnt lgkmcnt(0)
	s_barrier
	s_waitcnt lgkmcnt(0)
	v_mfma_f32_16x16x32_f16 v[130:133], v[144:147], v[202:205], 0
	v_mfma_f32_16x16x32_f16 v[126:129], v[178:181], v[202:205], 0
	v_mfma_f32_16x16x32_f16 v[114:117], v[144:147], v[210:213], 0
	v_mfma_f32_16x16x32_f16 v[110:113], v[178:181], v[210:213], 0
	v_mfma_f32_16x16x32_f16 v[98:101], v[144:147], v[218:221], 0
	v_mfma_f32_16x16x32_f16 v[94:97], v[178:181], v[218:221], 0
	v_mfma_f32_16x16x32_f16 v[82:85], v[144:147], v[226:229], 0
	v_mfma_f32_16x16x32_f16 v[78:81], v[178:181], v[226:229], 0
	v_mfma_f32_16x16x32_f16 v[130:133], v[152:155], v[206:209], v[130:133]
	v_mfma_f32_16x16x32_f16 v[126:129], v[182:185], v[206:209], v[126:129]
	v_mfma_f32_16x16x32_f16 v[114:117], v[152:155], v[214:217], v[114:117]
	v_mfma_f32_16x16x32_f16 v[110:113], v[182:185], v[214:217], v[110:113]
	v_mfma_f32_16x16x32_f16 v[98:101], v[152:155], v[222:225], v[98:101]
	v_mfma_f32_16x16x32_f16 v[94:97], v[182:185], v[222:225], v[94:97]
	v_mfma_f32_16x16x32_f16 v[82:85], v[152:155], v[230:233], v[82:85]
	v_mfma_f32_16x16x32_f16 v[78:81], v[182:185], v[230:233], v[78:81]
	v_mfma_f32_16x16x32_f16 v[122:125], v[186:189], v[202:205], 0
	v_mfma_f32_16x16x32_f16 v[118:121], v[194:197], v[202:205], 0
	v_mfma_f32_16x16x32_f16 v[106:109], v[186:189], v[210:213], 0
	v_mfma_f32_16x16x32_f16 v[102:105], v[194:197], v[210:213], 0
	v_mfma_f32_16x16x32_f16 v[90:93], v[186:189], v[218:221], 0
	v_mfma_f32_16x16x32_f16 v[86:89], v[194:197], v[218:221], 0
	v_mfma_f32_16x16x32_f16 v[74:77], v[186:189], v[226:229], 0
	v_mfma_f32_16x16x32_f16 v[70:73], v[194:197], v[226:229], 0
	v_mfma_f32_16x16x32_f16 v[122:125], v[190:193], v[206:209], v[122:125]
	v_mfma_f32_16x16x32_f16 v[118:121], v[198:201], v[206:209], v[118:121]
	v_mfma_f32_16x16x32_f16 v[106:109], v[190:193], v[214:217], v[106:109]
	v_mfma_f32_16x16x32_f16 v[102:105], v[198:201], v[214:217], v[102:105]
	v_mfma_f32_16x16x32_f16 v[90:93], v[190:193], v[222:225], v[90:93]
	v_mfma_f32_16x16x32_f16 v[86:89], v[198:201], v[222:225], v[86:89]
	v_mfma_f32_16x16x32_f16 v[74:77], v[190:193], v[230:233], v[74:77]
	v_mfma_f32_16x16x32_f16 v[70:73], v[198:201], v[230:233], v[70:73]
	s_barrier
	s_add_i32 s44, s44, s30
	v_lshl_add_u64 v[234:235], s[22:23], 0, v[0:1]
	s_mov_b32 m0, s44
	ds_read_b128 v[202:205], v151 offset:16384
	ds_read_b128 v[206:209], v151 offset:17408
	ds_read_b128 v[210:213], v151 offset:18432
	ds_read_b128 v[214:217], v151 offset:19456
	ds_read_b128 v[218:221], v151 offset:20480
	ds_read_b128 v[222:225], v151 offset:21504
	ds_read_b128 v[226:229], v151 offset:22528
	ds_read_b128 v[230:233], v151 offset:23552
	global_load_lds_dwordx4 v[234:235], off
	s_add_i32 m0, s44, 0x2000
	s_add_u32 s44, s22, 0x40000
	v_lshl_add_u64 v[236:237], s[22:23], 0, v[138:139]
	s_addc_u32 s45, s23, 0
	s_add_i32 s46, s46, s30
	global_load_lds_dwordx4 v[236:237], off
	v_lshl_add_u64 v[238:239], s[44:45], 0, v[0:1]
	s_mov_b32 m0, s46
	v_lshl_add_u64 v[240:241], s[26:27], 0, v[134:135]
	global_load_lds_dwordx4 v[238:239], off
	v_lshl_add_u64 v[238:239], s[44:45], 0, v[138:139]
	s_add_i32 m0, s46, 0x2000
	s_nop 0
	global_load_lds_dwordx4 v[238:239], off
	v_lshl_add_u64 v[238:239], s[26:27], 0, v[2:3]
	s_mov_b32 m0, s17
	s_nop 0
	global_load_lds_dwordx4 v[238:239], off
	s_mov_b32 m0, s19
	s_nop 0
	global_load_lds_dwordx4 v[240:241], off
	s_waitcnt vmcnt(24)
	s_waitcnt lgkmcnt(0)
	s_barrier
; #define STAGE(bufoff, gbase, voff) do { _Pragma("unroll") for (int _i = 0; _i < 2; ++_i) \
;     __builtin_amdgcn_global_load_lds((const unsigned*)((const char*)(gbase) + (voff)[_i]), (LAS unsigned*)(lds + (bufoff) + ldsw + _i * 8192), 16, 0, 0); } while (0)
; #define LDA(dst, b, h) do { _Pragma("unroll") for (int m = 0; m < 4; ++m) _Pragma("unroll") for (int k = 0; k < 2; ++k) dst[m][k] = *(const LAS half8*)(lds + SA(b, h) + aoff + m * 2048 + k * 1024); } while (0)
; #define LDB(dst, b, h) do { _Pragma("unroll") for (int n = 0; n < 2; ++n) _Pragma("unroll") for (int k = 0; k < 2; ++k) dst[n][k] = *(const LAS half8*)(lds + SB(b, h) + boff + n * 2048 + k * 1024); } while (0)
; #define MMA(ai, bj, At_, Bt_) do { __builtin_amdgcn_s_setprio(1); \
;     _Pragma("unroll") for (int m = 0; m < 4; ++m) _Pragma("unroll") for (int n = 0; n < 2; ++n) _Pragma("unroll") for (int k = 0; k < 2; ++k) \
;       acc[ai][bj][m][n] = MFMA16(Bt_[n][k], At_[m][k], acc[ai][bj][m][n]); \
;     __builtin_amdgcn_s_setprio(0); } while (0)
; #define WAIT_V(n) asm volatile("s_waitcnt vmcnt(" #n ")" ::: "memory")
; #define WAIT_L(n) asm volatile("s_waitcnt lgkmcnt(" #n ")" ::: "memory")
; #define BAR __builtin_amdgcn_s_barrier()
; #define SCHED __builtin_amdgcn_sched_barrier(0)
; template <int EPI>
; DI void gemm_phase(const int wid_s, const h16* __restrict__ A, const h16* __restrict__ Bt, const int N, const int K, const EpiArgs ea) {
;     ...
;       WAIT_V(8); WAIT_L(0); BAR; MMA(1, 0, At, B0); MMA(1, 1, At, B1); BAR; SCHED;
;       LDB(B0, 1, 0); LDB(B1, 1, 1); SCHED; LDA(At, 1, 0); STAGE(SA(0, 1), a2 + hstep, voffA);
;       WAIT_V(8); WAIT_L(0); BAR; MMA(0, 0, At, B0); MMA(0, 1, At, B1); BAR; SCHED;
	s_waitcnt lgkmcnt(0)
	v_mfma_f32_16x16x32_f16 v[66:69], v[144:147], v[202:205], 0
	v_mfma_f32_16x16x32_f16 v[62:65], v[178:181], v[202:205], 0
	v_mfma_f32_16x16x32_f16 v[50:53], v[144:147], v[210:213], 0
	v_mfma_f32_16x16x32_f16 v[46:49], v[178:181], v[210:213], 0
	v_mfma_f32_16x16x32_f16 v[34:37], v[144:147], v[218:221], 0
	v_mfma_f32_16x16x32_f16 v[30:33], v[178:181], v[218:221], 0
	v_mfma_f32_16x16x32_f16 v[18:21], v[144:147], v[226:229], 0
	v_mfma_f32_16x16x32_f16 v[14:17], v[178:181], v[226:229], 0
	v_mfma_f32_16x16x32_f16 v[66:69], v[152:155], v[206:209], v[66:69]
	v_mfma_f32_16x16x32_f16 v[62:65], v[182:185], v[206:209], v[62:65]
	v_mfma_f32_16x16x32_f16 v[50:53], v[152:155], v[214:217], v[50:53]
	v_mfma_f32_16x16x32_f16 v[46:49], v[182:185], v[214:217], v[46:49]
	v_mfma_f32_16x16x32_f16 v[34:37], v[152:155], v[222:225], v[34:37]
	v_mfma_f32_16x16x32_f16 v[30:33], v[182:185], v[222:225], v[30:33]
	v_mfma_f32_16x16x32_f16 v[18:21], v[152:155], v[230:233], v[18:21]
	v_mfma_f32_16x16x32_f16 v[14:17], v[182:185], v[230:233], v[14:17]
	v_mfma_f32_16x16x32_f16 v[58:61], v[186:189], v[202:205], 0
	v_mfma_f32_16x16x32_f16 v[54:57], v[194:197], v[202:205], 0
	v_mfma_f32_16x16x32_f16 v[42:45], v[186:189], v[210:213], 0
	v_mfma_f32_16x16x32_f16 v[38:41], v[194:197], v[210:213], 0
	v_mfma_f32_16x16x32_f16 v[26:29], v[186:189], v[218:221], 0
	v_mfma_f32_16x16x32_f16 v[22:25], v[194:197], v[218:221], 0
	v_mfma_f32_16x16x32_f16 v[10:13], v[186:189], v[226:229], 0
	v_mfma_f32_16x16x32_f16 v[6:9], v[194:197], v[226:229], 0
	v_mfma_f32_16x16x32_f16 v[58:61], v[190:193], v[206:209], v[58:61]
	v_mfma_f32_16x16x32_f16 v[54:57], v[198:201], v[206:209], v[54:57]
	v_mfma_f32_16x16x32_f16 v[42:45], v[190:193], v[214:217], v[42:45]
	v_mfma_f32_16x16x32_f16 v[38:41], v[198:201], v[214:217], v[38:41]
	v_mfma_f32_16x16x32_f16 v[26:29], v[190:193], v[222:225], v[26:29]
	v_mfma_f32_16x16x32_f16 v[22:25], v[198:201], v[222:225], v[22:25]
	v_mfma_f32_16x16x32_f16 v[10:13], v[190:193], v[230:233], v[10:13]
	v_mfma_f32_16x16x32_f16 v[6:9], v[198:201], v[230:233], v[6:9]
	s_barrier
	s_add_i32 s44, 0, 0x18000
	v_add_u32_e32 v177, s44, v148
	s_add_i32 s45, 0, 0x1c000
	ds_read_b128 v[144:147], v177
	ds_read_b128 v[152:155], v177 offset:1024
	ds_read_b128 v[178:181], v177 offset:2048
	ds_read_b128 v[182:185], v177 offset:3072
	v_add_u32_e32 v177, s45, v148
	ds_read_b128 v[186:189], v177
	ds_read_b128 v[190:193], v177 offset:1024
	ds_read_b128 v[194:197], v177 offset:2048
	ds_read_b128 v[198:201], v177 offset:3072
	s_add_u32 s26, s26, 0x40000
	s_addc_u32 s27, s27, 0
	s_mov_b32 m0, s31
	v_lshl_add_u64 v[242:243], s[26:27], 0, v[2:3]
	ds_read_b128 v[202:205], v151 offset:32768
	ds_read_b128 v[206:209], v151 offset:33792
	ds_read_b128 v[210:213], v151 offset:34816
	ds_read_b128 v[214:217], v151 offset:35840
	ds_read_b128 v[218:221], v151 offset:36864
	ds_read_b128 v[222:225], v151 offset:37888
	ds_read_b128 v[226:229], v151 offset:38912
	ds_read_b128 v[230:233], v151 offset:39936
	global_load_lds_dwordx4 v[242:243], off
	v_lshl_add_u64 v[242:243], s[26:27], 0, v[134:135]
	s_mov_b32 m0, s38
	s_nop 0
	global_load_lds_dwordx4 v[242:243], off
	s_waitcnt vmcnt(8)
	s_waitcnt lgkmcnt(0)
	s_barrier
	s_waitcnt lgkmcnt(0)
	v_mfma_f32_16x16x32_f16 v[130:133], v[144:147], v[202:205], v[130:133]
	v_mfma_f32_16x16x32_f16 v[126:129], v[178:181], v[202:205], v[126:129]
	v_mfma_f32_16x16x32_f16 v[114:117], v[144:147], v[210:213], v[114:117]
	v_mfma_f32_16x16x32_f16 v[110:113], v[178:181], v[210:213], v[110:113]
	v_mfma_f32_16x16x32_f16 v[98:101], v[144:147], v[218:221], v[98:101]
	v_mfma_f32_16x16x32_f16 v[94:97], v[178:181], v[218:221], v[94:97]
	v_mfma_f32_16x16x32_f16 v[82:85], v[144:147], v[226:229], v[82:85]
	v_mfma_f32_16x16x32_f16 v[78:81], v[178:181], v[226:229], v[78:81]
	v_mfma_f32_16x16x32_f16 v[130:133], v[152:155], v[206:209], v[130:133]
	v_mfma_f32_16x16x32_f16 v[126:129], v[182:185], v[206:209], v[126:129]
	v_mfma_f32_16x16x32_f16 v[114:117], v[152:155], v[214:217], v[114:117]
	v_mfma_f32_16x16x32_f16 v[110:113], v[182:185], v[214:217], v[110:113]
	v_mfma_f32_16x16x32_f16 v[98:101], v[152:155], v[222:225], v[98:101]
	v_mfma_f32_16x16x32_f16 v[94:97], v[182:185], v[222:225], v[94:97]
	v_mfma_f32_16x16x32_f16 v[82:85], v[152:155], v[230:233], v[82:85]
	v_mfma_f32_16x16x32_f16 v[78:81], v[182:185], v[230:233], v[78:81]
	v_mfma_f32_16x16x32_f16 v[122:125], v[186:189], v[202:205], v[122:125]
	v_mfma_f32_16x16x32_f16 v[118:121], v[194:197], v[202:205], v[118:121]
	v_mfma_f32_16x16x32_f16 v[106:109], v[186:189], v[210:213], v[106:109]
	v_mfma_f32_16x16x32_f16 v[102:105], v[194:197], v[210:213], v[102:105]
	v_mfma_f32_16x16x32_f16 v[90:93], v[186:189], v[218:221], v[90:93]
	v_mfma_f32_16x16x32_f16 v[86:89], v[194:197], v[218:221], v[86:89]
	v_mfma_f32_16x16x32_f16 v[74:77], v[186:189], v[226:229], v[74:77]
	v_mfma_f32_16x16x32_f16 v[70:73], v[194:197], v[226:229], v[70:73]
	v_mfma_f32_16x16x32_f16 v[122:125], v[190:193], v[206:209], v[122:125]
	v_mfma_f32_16x16x32_f16 v[118:121], v[198:201], v[206:209], v[118:121]
	v_mfma_f32_16x16x32_f16 v[106:109], v[190:193], v[214:217], v[106:109]
	v_mfma_f32_16x16x32_f16 v[102:105], v[198:201], v[214:217], v[102:105]
	v_mfma_f32_16x16x32_f16 v[90:93], v[190:193], v[222:225], v[90:93]
	v_mfma_f32_16x16x32_f16 v[86:89], v[198:201], v[222:225], v[86:89]
	v_mfma_f32_16x16x32_f16 v[74:77], v[190:193], v[230:233], v[74:77]
	v_mfma_f32_16x16x32_f16 v[70:73], v[198:201], v[230:233], v[70:73]
	s_barrier
; #define STAGE(bufoff, gbase, voff) do { _Pragma("unroll") for (int _i = 0; _i < 2; ++_i) \
;     __builtin_amdgcn_global_load_lds((const unsigned*)((const char*)(gbase) + (voff)[_i]), (LAS unsigned*)(lds + (bufoff) + ldsw + _i * 8192), 16, 0, 0); } while (0)
; #define LDA(dst, b, h) do { _Pragma("unroll") for (int m = 0; m < 4; ++m) _Pragma("unroll") for (int k = 0; k < 2; ++k) dst[m][k] = *(const LAS half8*)(lds + SA(b, h) + aoff + m * 2048 + k * 1024); } while (0)
; #define MMA(ai, bj, At_, Bt_) do { __builtin_amdgcn_s_setprio(1); \
;     _Pragma("unroll") for (int m = 0; m < 4; ++m) _Pragma("unroll") for (int n = 0; n < 2; ++n) _Pragma("unroll") for (int k = 0; k < 2; ++k) \
;       acc[ai][bj][m][n] = MFMA16(Bt_[n][k], At_[m][k], acc[ai][bj][m][n]); \
;     __builtin_amdgcn_s_setprio(0); } while (0)
; #define WAIT_V(n) asm volatile("s_waitcnt vmcnt(" #n ")" ::: "memory")
; #define WAIT_L(n) asm volatile("s_waitcnt lgkmcnt(" #n ")" ::: "memory")
; #define BAR __builtin_amdgcn_s_barrier()
; #define SCHED __builtin_amdgcn_sched_barrier(0)
; template <int EPI>
; DI void gemm_phase(const int wid_s, const h16* __restrict__ A, const h16* __restrict__ Bt, const int N, const int K, const EpiArgs ea) {
;     ...
;       LDA(At, 1, 1); STAGE(SB(1, 0), b3, voffB); STAGE(SB(1, 1), b3 + hstep, voffB); STAGE(SA(1, 0), a3, voffA);
;       WAIT_V(8); WAIT_L(0); BAR; MMA(1, 0, At, B0); MMA(1, 1, At, B1); BAR; SCHED;
;     }
	s_add_i32 s26, s44, s30
	v_lshl_add_u64 v[234:235], v[234:235], 0, s[36:37]
	s_mov_b32 m0, s26
	ds_read_b128 v[202:205], v151 offset:49152
	ds_read_b128 v[206:209], v151 offset:50176
	ds_read_b128 v[210:213], v151 offset:51200
	ds_read_b128 v[214:217], v151 offset:52224
	ds_read_b128 v[218:221], v151 offset:53248
	ds_read_b128 v[222:225], v151 offset:54272
	ds_read_b128 v[226:229], v151 offset:55296
	ds_read_b128 v[230:233], v151 offset:56320
	global_load_lds_dwordx4 v[234:235], off
	s_add_i32 m0, s26, 0x2000
	s_add_u32 s22, s22, 0x40080
	v_lshl_add_u64 v[234:235], v[236:237], 0, s[36:37]
	s_addc_u32 s23, s23, 0
	s_add_i32 s26, s45, s30
	global_load_lds_dwordx4 v[234:235], off
	v_lshl_add_u64 v[234:235], s[22:23], 0, v[0:1]
	s_mov_b32 m0, s26
	s_nop 0
	global_load_lds_dwordx4 v[234:235], off
	v_lshl_add_u64 v[234:235], s[22:23], 0, v[138:139]
	s_add_i32 m0, s26, 0x2000
	s_nop 0
	global_load_lds_dwordx4 v[234:235], off
	v_lshl_add_u64 v[234:235], v[238:239], 0, s[36:37]
	s_mov_b32 m0, s39
	s_nop 0
	global_load_lds_dwordx4 v[234:235], off
	v_lshl_add_u64 v[234:235], v[240:241], 0, s[36:37]
	s_mov_b32 m0, s40
	s_nop 0
	global_load_lds_dwordx4 v[234:235], off
	s_waitcnt vmcnt(8)
	s_waitcnt lgkmcnt(0)
	s_barrier
	s_waitcnt lgkmcnt(0)
	v_mfma_f32_16x16x32_f16 v[66:69], v[144:147], v[202:205], v[66:69]
	v_mfma_f32_16x16x32_f16 v[62:65], v[178:181], v[202:205], v[62:65]
	v_mfma_f32_16x16x32_f16 v[50:53], v[144:147], v[210:213], v[50:53]
	v_mfma_f32_16x16x32_f16 v[46:49], v[178:181], v[210:213], v[46:49]
	v_mfma_f32_16x16x32_f16 v[34:37], v[144:147], v[218:221], v[34:37]
	v_mfma_f32_16x16x32_f16 v[30:33], v[178:181], v[218:221], v[30:33]
	v_mfma_f32_16x16x32_f16 v[18:21], v[144:147], v[226:229], v[18:21]
	v_mfma_f32_16x16x32_f16 v[14:17], v[178:181], v[226:229], v[14:17]
	v_mfma_f32_16x16x32_f16 v[66:69], v[152:155], v[206:209], v[66:69]
	v_mfma_f32_16x16x32_f16 v[62:65], v[182:185], v[206:209], v[62:65]
	v_mfma_f32_16x16x32_f16 v[50:53], v[152:155], v[214:217], v[50:53]
	v_mfma_f32_16x16x32_f16 v[46:49], v[182:185], v[214:217], v[46:49]
	v_mfma_f32_16x16x32_f16 v[34:37], v[152:155], v[222:225], v[34:37]
	v_mfma_f32_16x16x32_f16 v[30:33], v[182:185], v[222:225], v[30:33]
	v_mfma_f32_16x16x32_f16 v[18:21], v[152:155], v[230:233], v[18:21]
	v_mfma_f32_16x16x32_f16 v[14:17], v[182:185], v[230:233], v[14:17]
	v_mfma_f32_16x16x32_f16 v[58:61], v[186:189], v[202:205], v[58:61]
	v_mfma_f32_16x16x32_f16 v[54:57], v[194:197], v[202:205], v[54:57]
	v_mfma_f32_16x16x32_f16 v[42:45], v[186:189], v[210:213], v[42:45]
	v_mfma_f32_16x16x32_f16 v[38:41], v[194:197], v[210:213], v[38:41]
	v_mfma_f32_16x16x32_f16 v[26:29], v[186:189], v[218:221], v[26:29]
	v_mfma_f32_16x16x32_f16 v[22:25], v[194:197], v[218:221], v[22:25]
	v_mfma_f32_16x16x32_f16 v[10:13], v[186:189], v[226:229], v[10:13]
	v_mfma_f32_16x16x32_f16 v[6:9], v[194:197], v[226:229], v[6:9]
	v_mfma_f32_16x16x32_f16 v[58:61], v[190:193], v[206:209], v[58:61]
	v_mfma_f32_16x16x32_f16 v[54:57], v[198:201], v[206:209], v[54:57]
	v_mfma_f32_16x16x32_f16 v[42:45], v[190:193], v[214:217], v[42:45]
	v_mfma_f32_16x16x32_f16 v[38:41], v[198:201], v[214:217], v[38:41]
	v_mfma_f32_16x16x32_f16 v[26:29], v[190:193], v[222:225], v[26:29]
	v_mfma_f32_16x16x32_f16 v[22:25], v[198:201], v[222:225], v[22:25]
	v_mfma_f32_16x16x32_f16 v[10:13], v[190:193], v[230:233], v[10:13]
	v_mfma_f32_16x16x32_f16 v[6:9], v[198:201], v[230:233], v[6:9]
	s_barrier
	s_add_i32 s43, s43, 2
	s_add_u32 s41, s41, 0x100
	s_addc_u32 s42, s42, 0
	s_add_u32 s20, s20, 0x100
	s_addc_u32 s21, s21, 0
	s_cmp_gt_u32 s43, 13

; __device__ __forceinline__ int opaque_tid(int wid_s) { int t = wid_s * 64 + lane_id_hw(); asm volatile("" : "+v"(t)); return t; }
; #define STAGE(bufoff, gbase, voff) do { _Pragma("unroll") for (int _i = 0; _i < 2; ++_i) \
;     __builtin_amdgcn_global_load_lds((const unsigned*)((const char*)(gbase) + (voff)[_i]), (LAS unsigned*)(lds + (bufoff) + ldsw + _i * 8192), 16, 0, 0); } while (0)
; #define WAIT_V(n) asm volatile("s_waitcnt vmcnt(" #n ")" ::: "memory")
; #define BAR __builtin_amdgcn_s_barrier()
; template <int EPI>
; DI void gemm_phase(const int wid_s, const h16* __restrict__ A, const h16* __restrict__ Bt, const int N, const int K, const EpiArgs ea) {
;     ...
;   const int tid = opaque_tid(wid_s), wid = __builtin_amdgcn_readfirstlane(tid >> 6), lane = tid & 63, wr = wid >> 2, wc = wid & 3, fr = lane & 15, fq = lane >> 4;
;   unsigned voffA[2], voffB[2];
; #pragma unroll
;   for (int i = 0; i < 2; ++i) { int R, C; stage_rc(tid * 16 + i * 8192, R, C); const int Rb = (R & ~31) + perm32(R & 31);
;     voffA[i] = (unsigned)(R * K + C) * 2u; voffB[i] = (unsigned)(Rb * K + C) * 2u; }
;   const size_t kstep = (size_t)(BK * 2), hstep = (size_t)HALF * K * 2;
;   const unsigned ldsw = (unsigned)wid * 1024u;
;   const int aoff = lds_byte(wr * 64 + fr, fq * 8), boff = lds_byte(wc * 32 + fr, fq * 8);
;     ...
;   STAGE(SB(0, 0), cB, voffB); STAGE(SB(0, 1), cB + hstep, voffB); STAGE(SA(0, 0), cA, voffA); STAGE(SA(0, 1), cA + hstep, voffA);
;   if (wr == 1) BAR;
;   WAIT_V(2); BAR;
;   STAGE(SB(1, 0), cB + kstep, voffB); STAGE(SA(1, 0), cA + kstep, voffA); STAGE(SB(1, 1), cB + hstep + kstep, voffB);
;   WAIT_V(6); BAR;
.LBB0_380:
	s_lshl_b32 s8, s8, 5
	s_and_b32 s8, s8, 0x60
	s_add_i32 m0, s13, 0x18000
	v_lshl_add_u64 v[12:13], v[12:13], 0, s[36:37]
	s_lshl_b32 s9, s7, 13
	s_lshl_b32 s10, s8, 7
	s_waitcnt vmcnt(2)
	s_barrier
	global_load_lds_dwordx4 v[12:13], off
	v_lshl_add_u64 v[10:11], v[10:11], 0, s[36:37]
	s_add_i32 m0, s13, 0x1a000
	s_add_i32 s39, s13, 0x8000
	s_add_i32 s40, s13, 0xa000
	global_load_lds_dwordx4 v[10:11], off
	v_lshl_add_u64 v[6:7], v[6:7], 0, s[36:37]
	s_mov_b32 m0, s39
	s_add_u32 s4, s4, 0x40080
	global_load_lds_dwordx4 v[6:7], off
	v_lshl_add_u64 v[6:7], v[8:9], 0, s[36:37]
	s_mov_b32 m0, s40
	s_addc_u32 s5, s5, 0
	global_load_lds_dwordx4 v[6:7], off
	s_add_i32 m0, s13, 0x1c000
	v_lshl_add_u64 v[6:7], s[4:5], 0, v[0:1]
	global_load_lds_dwordx4 v[6:7], off
	v_lshl_add_u64 v[6:7], s[4:5], 0, v[2:3]
	s_add_i32 m0, s13, 0x1e000
	s_cmpk_lt_u32 s6, 0x100
	global_load_lds_dwordx4 v[6:7], off
	v_lshrrev_b32_e32 v7, 1, v14
	v_and_b32_e32 v7, 24, v7
	v_and_b32_e32 v6, 15, v14
	v_lshlrev_b32_e32 v8, 1, v7
	v_lshl_or_b32 v5, s7, 6, v6
	v_lshl_or_b32 v6, v6, 6, v8
	v_lshlrev_b32_e32 v8, 2, v14
	v_and_b32_e32 v8, 32, v8
	v_bitop3_b32 v9, v6, s9, v8 bitop3:0xde
	v_bitop3_b32 v148, v6, s10, v8 bitop3:0xde
	v_lshlrev_b32_e32 v6, 14, v15
	v_and_b32_e32 v6, 0xffff8000, v6
	v_or_b32_e32 v150, s8, v7
	v_lshl_add_u32 v6, v16, 11, v6
	v_and_b32_e32 v7, 1, v15
	v_lshl_or_b32 v6, v7, 6, v6
	v_readlane_b32 s6, v249, 25
	v_lshl_add_u32 v6, v17, 1, v6
	v_mov_b32_e32 v7, v1
	v_readlane_b32 s7, v249, 26
	s_waitcnt vmcnt(0)
	s_cselect_b64 s[4:5], -1, 0
	v_add_u32_e32 v151, 0, v9
	v_lshl_add_u64 v[140:141], s[6:7], 0, v[6:7]
	v_lshlrev_b32_e32 v6, 14, v19
	v_and_b32_e32 v6, 0xffff8000, v6
	v_lshl_add_u32 v6, v18, 11, v6
	v_and_b32_e32 v7, 1, v19
	v_lshl_or_b32 v6, v7, 6, v6
	v_lshl_add_u32 v6, v20, 1, v6
	v_mov_b32_e32 v7, v1
	v_lshl_add_u64 v[142:143], s[6:7], 0, v[6:7]
	s_barrier
	s_branch .LBB0_383

; #define STAGE(bufoff, gbase, voff) do { _Pragma("unroll") for (int _i = 0; _i < 2; ++_i) \
;     __builtin_amdgcn_global_load_lds((const unsigned*)((const char*)(gbase) + (voff)[_i]), (LAS unsigned*)(lds + (bufoff) + ldsw + _i * 8192), 16, 0, 0); } while (0)
; #define LDA(dst, b, h) do { _Pragma("unroll") for (int m = 0; m < 4; ++m) _Pragma("unroll") for (int k = 0; k < 2; ++k) dst[m][k] = *(const LAS half8*)(lds + SA(b, h) + aoff + m * 2048 + k * 1024); } while (0)
; #define LDB(dst, b, h) do { _Pragma("unroll") for (int n = 0; n < 2; ++n) _Pragma("unroll") for (int k = 0; k < 2; ++k) dst[n][k] = *(const LAS half8*)(lds + SB(b, h) + boff + n * 2048 + k * 1024); } while (0)
; #define MMA(ai, bj, At_, Bt_) do { __builtin_amdgcn_s_setprio(1); \
;     _Pragma("unroll") for (int m = 0; m < 4; ++m) _Pragma("unroll") for (int n = 0; n < 2; ++n) _Pragma("unroll") for (int k = 0; k < 2; ++k) \
;       acc[ai][bj][m][n] = MFMA16(Bt_[n][k], At_[m][k], acc[ai][bj][m][n]); \
;     __builtin_amdgcn_s_setprio(0); } while (0)
; #define WAIT_V(n) asm volatile("s_waitcnt vmcnt(" #n ")" ::: "memory")
; #define WAIT_L(n) asm volatile("s_waitcnt lgkmcnt(" #n ")" ::: "memory")
; #define BAR __builtin_amdgcn_s_barrier()
; template <int EPI>
; DI void gemm_phase(const int wid_s, const h16* __restrict__ A, const h16* __restrict__ Bt, const int N, const int K, const EpiArgs ea) {
;     ...
;     const int Ln = L + (int)gridDim.x;
;     const bool has_next = Ln < nwg;
;     int nbrow = brow, nbcol = bcol;
;     if (has_next) TILE_RC(Ln, nbrow, nbcol);
;     const char* nA = (const char*)A + (size_t)nbrow * K * 2;
;     const char* nB = (const char*)Bt + (size_t)nbcol * K * 2;
;     for (int t = 0; t < nt; t += 2) {
;       const bool last = (t == nt - 2);
;       const char* a1 = cA + (size_t)(t + 1) * kstep;
;       const char* a2 = last ? nA : cA + (size_t)(t + 2) * kstep; const char* b2 = last ? nB : cB + (size_t)(t + 2) * kstep;
;       const char* a3 = a2 + kstep; const char* b3 = b2 + kstep;
;       LDB(B0, 0, 0); LDB(B1, 0, 1); SCHED; LDA(At, 0, 0); STAGE(SA(1, 1), a1 + hstep, voffA);
;       WAIT_V(8); WAIT_L(0); BAR; MMA(0, 0, At, B0); MMA(0, 1, At, B1); BAR; SCHED;
;       LDA(At, 0, 1); STAGE(SB(0, 0), b2, voffB); STAGE(SB(0, 1), b2 + hstep, voffB); STAGE(SA(0, 0), a2, voffA);
;       WAIT_V(8); WAIT_L(0); BAR; MMA(1, 0, At, B0); MMA(1, 1, At, B1); BAR; SCHED;
.LBB0_385:
	s_ashr_i32 s9, s8, 31
	s_lshl_b64 s[16:17], s[8:9], 11
	s_add_u32 s9, s92, s16
	s_addc_u32 s41, s93, s17
	s_ashr_i32 s11, s10, 31
	s_lshl_b64 s[18:19], s[10:11], 11
	v_readlane_b32 s11, v249, 29
	s_add_u32 s11, s11, s18
	v_readlane_b32 s26, v249, 31
	s_addc_u32 s42, s26, s19
	v_readlane_b32 s26, v249, 30
	s_add_u32 s43, s26, s22
	v_readlane_b32 s22, v249, 32
	s_addc_u32 s44, s22, s23
	s_add_u32 s45, s86, s20
	v_mov_b32_e32 v6, 0
	v_lshl_add_u64 v[144:145], v[140:141], 0, s[20:21]
	v_lshl_add_u64 v[146:147], v[142:143], 0, s[20:21]
	s_addc_u32 s46, s87, s21
	s_mov_b32 s47, -2
	s_mov_b64 s[20:21], 0
	s_add_u32 s22, s45, s20
	s_addc_u32 s23, s46, s21
	s_add_u32 s22, s22, 0x520e100
	s_addc_u32 s23, s23, 0
	s_add_u32 s48, s43, s20
	s_addc_u32 s49, s44, s21
	s_add_i32 s50, 0, 0x10000
	s_cmpk_eq_i32 s20, 0x700
	s_cselect_b32 s27, s41, s23
	s_cselect_b32 s26, s9, s22
	v_add_u32_e32 v177, s50, v148
	s_cselect_b32 s23, s42, s49
	s_cselect_b32 s22, s11, s48
	s_add_i32 s51, 0, 0x14000
	ds_read_b128 v[152:155], v177
	ds_read_b128 v[178:181], v177 offset:1024
	ds_read_b128 v[182:185], v177 offset:2048
	ds_read_b128 v[186:189], v177 offset:3072
	v_add_u32_e32 v177, s51, v148
	ds_read_b128 v[190:193], v177
	ds_read_b128 v[194:197], v177 offset:1024
	ds_read_b128 v[198:201], v177 offset:2048
	ds_read_b128 v[202:205], v177 offset:3072
	v_lshl_add_u64 v[238:239], v[146:147], 0, s[20:21]
	s_add_i32 m0, s13, 0xc000
	ds_read_b128 v[206:209], v151
	ds_read_b128 v[210:213], v151 offset:1024
	ds_read_b128 v[214:217], v151 offset:2048
	ds_read_b128 v[218:221], v151 offset:3072
	ds_read_b128 v[222:225], v151 offset:4096
	ds_read_b128 v[226:229], v151 offset:5120
	ds_read_b128 v[230:233], v151 offset:6144
	ds_read_b128 v[234:237], v151 offset:7168
	global_load_lds_dwordx4 v[238:239], off
	v_lshl_add_u64 v[238:239], v[144:145], 0, s[20:21]
	s_add_i32 m0, s13, 0xe000
	s_nop 0
	global_load_lds_dwordx4 v[238:239], off
	s_waitcnt vmcnt(24)
	s_waitcnt lgkmcnt(0)
	s_barrier
	s_waitcnt lgkmcnt(0)
	v_mfma_f32_16x16x32_f16 v[130:133], v[152:155], v[206:209], 0
	v_mfma_f32_16x16x32_f16 v[126:129], v[182:185], v[206:209], 0
	v_mfma_f32_16x16x32_f16 v[122:125], v[152:155], v[214:217], 0
	v_mfma_f32_16x16x32_f16 v[118:121], v[182:185], v[214:217], 0
	v_mfma_f32_16x16x32_f16 v[106:109], v[152:155], v[222:225], 0
	v_mfma_f32_16x16x32_f16 v[102:105], v[182:185], v[222:225], 0
	v_mfma_f32_16x16x32_f16 v[90:93], v[152:155], v[230:233], 0
	v_mfma_f32_16x16x32_f16 v[86:89], v[182:185], v[230:233], 0
	v_mfma_f32_16x16x32_f16 v[130:133], v[178:181], v[210:213], v[130:133]
	v_mfma_f32_16x16x32_f16 v[126:129], v[186:189], v[210:213], v[126:129]
	v_mfma_f32_16x16x32_f16 v[122:125], v[178:181], v[218:221], v[122:125]
	v_mfma_f32_16x16x32_f16 v[118:121], v[186:189], v[218:221], v[118:121]
	v_mfma_f32_16x16x32_f16 v[106:109], v[178:181], v[226:229], v[106:109]
	v_mfma_f32_16x16x32_f16 v[102:105], v[186:189], v[226:229], v[102:105]
	v_mfma_f32_16x16x32_f16 v[90:93], v[178:181], v[234:237], v[90:93]
	v_mfma_f32_16x16x32_f16 v[86:89], v[186:189], v[234:237], v[86:89]
	v_mfma_f32_16x16x32_f16 v[114:117], v[190:193], v[206:209], 0
	v_mfma_f32_16x16x32_f16 v[110:113], v[198:201], v[206:209], 0
	v_mfma_f32_16x16x32_f16 v[98:101], v[190:193], v[214:217], 0
	v_mfma_f32_16x16x32_f16 v[94:97], v[198:201], v[214:217], 0
	v_mfma_f32_16x16x32_f16 v[82:85], v[190:193], v[222:225], 0
	v_mfma_f32_16x16x32_f16 v[78:81], v[198:201], v[222:225], 0
	v_mfma_f32_16x16x32_f16 v[74:77], v[190:193], v[230:233], 0
	v_mfma_f32_16x16x32_f16 v[70:73], v[198:201], v[230:233], 0
	v_mfma_f32_16x16x32_f16 v[114:117], v[194:197], v[210:213], v[114:117]
	v_mfma_f32_16x16x32_f16 v[110:113], v[202:205], v[210:213], v[110:113]
	v_mfma_f32_16x16x32_f16 v[98:101], v[194:197], v[218:221], v[98:101]
	v_mfma_f32_16x16x32_f16 v[94:97], v[202:205], v[218:221], v[94:97]
	v_mfma_f32_16x16x32_f16 v[82:85], v[194:197], v[226:229], v[82:85]
	v_mfma_f32_16x16x32_f16 v[78:81], v[202:205], v[226:229], v[78:81]
	v_mfma_f32_16x16x32_f16 v[74:77], v[194:197], v[234:237], v[74:77]
	v_mfma_f32_16x16x32_f16 v[70:73], v[202:205], v[234:237], v[70:73]
	s_barrier
	s_add_i32 s48, s50, s30
	v_lshl_add_u64 v[238:239], s[22:23], 0, v[0:1]
	s_mov_b32 m0, s48
	ds_read_b128 v[206:209], v151 offset:16384
	ds_read_b128 v[210:213], v151 offset:17408
	ds_read_b128 v[214:217], v151 offset:18432
	ds_read_b128 v[218:221], v151 offset:19456
	ds_read_b128 v[222:225], v151 offset:20480
	ds_read_b128 v[226:229], v151 offset:21504
	ds_read_b128 v[230:233], v151 offset:22528
	ds_read_b128 v[234:237], v151 offset:23552
	global_load_lds_dwordx4 v[238:239], off
	s_add_i32 m0, s48, 0x2000
	s_add_u32 s48, s22, 0x40000
	v_lshl_add_u64 v[240:241], s[22:23], 0, v[2:3]
	s_addc_u32 s49, s23, 0
	s_add_i32 s50, s51, s30
	global_load_lds_dwordx4 v[240:241], off
	v_lshl_add_u64 v[242:243], s[48:49], 0, v[0:1]
	s_mov_b32 m0, s50
	v_lshl_add_u64 v[244:245], s[26:27], 0, v[134:135]
	global_load_lds_dwordx4 v[242:243], off
	v_lshl_add_u64 v[242:243], s[48:49], 0, v[2:3]
	s_add_i32 m0, s50, 0x2000
	s_nop 0
	global_load_lds_dwordx4 v[242:243], off
	v_lshl_add_u64 v[242:243], s[26:27], 0, v[138:139]
	s_mov_b32 m0, s13
	s_nop 0
	global_load_lds_dwordx4 v[242:243], off
	s_mov_b32 m0, s15
	s_nop 0
	global_load_lds_dwordx4 v[244:245], off
	s_waitcnt vmcnt(24)
	s_waitcnt lgkmcnt(0)
	s_barrier
; #define STAGE(bufoff, gbase, voff) do { _Pragma("unroll") for (int _i = 0; _i < 2; ++_i) \
;     __builtin_amdgcn_global_load_lds((const unsigned*)((const char*)(gbase) + (voff)[_i]), (LAS unsigned*)(lds + (bufoff) + ldsw + _i * 8192), 16, 0, 0); } while (0)
; #define LDA(dst, b, h) do { _Pragma("unroll") for (int m = 0; m < 4; ++m) _Pragma("unroll") for (int k = 0; k < 2; ++k) dst[m][k] = *(const LAS half8*)(lds + SA(b, h) + aoff + m * 2048 + k * 1024); } while (0)
; #define LDB(dst, b, h) do { _Pragma("unroll") for (int n = 0; n < 2; ++n) _Pragma("unroll") for (int k = 0; k < 2; ++k) dst[n][k] = *(const LAS half8*)(lds + SB(b, h) + boff + n * 2048 + k * 1024); } while (0)
; #define MMA(ai, bj, At_, Bt_) do { __builtin_amdgcn_s_setprio(1); \
;     _Pragma("unroll") for (int m = 0; m < 4; ++m) _Pragma("unroll") for (int n = 0; n < 2; ++n) _Pragma("unroll") for (int k = 0; k < 2; ++k) \
;       acc[ai][bj][m][n] = MFMA16(Bt_[n][k], At_[m][k], acc[ai][bj][m][n]); \
;     __builtin_amdgcn_s_setprio(0); } while (0)
; #define WAIT_V(n) asm volatile("s_waitcnt vmcnt(" #n ")" ::: "memory")
; #define WAIT_L(n) asm volatile("s_waitcnt lgkmcnt(" #n ")" ::: "memory")
; #define BAR __builtin_amdgcn_s_barrier()
; #define SCHED __builtin_amdgcn_sched_barrier(0)
; template <int EPI>
; DI void gemm_phase(const int wid_s, const h16* __restrict__ A, const h16* __restrict__ Bt, const int N, const int K, const EpiArgs ea) {
;     ...
;       WAIT_V(8); WAIT_L(0); BAR; MMA(1, 0, At, B0); MMA(1, 1, At, B1); BAR; SCHED;
;       LDB(B0, 1, 0); LDB(B1, 1, 1); SCHED; LDA(At, 1, 0); STAGE(SA(0, 1), a2 + hstep, voffA);
;       WAIT_V(8); WAIT_L(0); BAR; MMA(0, 0, At, B0); MMA(0, 1, At, B1); BAR; SCHED;
	s_waitcnt lgkmcnt(0)
	v_mfma_f32_16x16x32_f16 v[66:69], v[152:155], v[206:209], 0
	v_mfma_f32_16x16x32_f16 v[62:65], v[182:185], v[206:209], 0
	v_mfma_f32_16x16x32_f16 v[58:61], v[152:155], v[214:217], 0
	v_mfma_f32_16x16x32_f16 v[54:57], v[182:185], v[214:217], 0
	v_mfma_f32_16x16x32_f16 v[42:45], v[152:155], v[222:225], 0
	v_mfma_f32_16x16x32_f16 v[38:41], v[182:185], v[222:225], 0
	v_mfma_f32_16x16x32_f16 v[26:29], v[152:155], v[230:233], 0
	v_mfma_f32_16x16x32_f16 v[22:25], v[182:185], v[230:233], 0
	v_mfma_f32_16x16x32_f16 v[66:69], v[178:181], v[210:213], v[66:69]
	v_mfma_f32_16x16x32_f16 v[62:65], v[186:189], v[210:213], v[62:65]
	v_mfma_f32_16x16x32_f16 v[58:61], v[178:181], v[218:221], v[58:61]
	v_mfma_f32_16x16x32_f16 v[54:57], v[186:189], v[218:221], v[54:57]
	v_mfma_f32_16x16x32_f16 v[42:45], v[178:181], v[226:229], v[42:45]
	v_mfma_f32_16x16x32_f16 v[38:41], v[186:189], v[226:229], v[38:41]
	v_mfma_f32_16x16x32_f16 v[26:29], v[178:181], v[234:237], v[26:29]
	v_mfma_f32_16x16x32_f16 v[22:25], v[186:189], v[234:237], v[22:25]
	v_mfma_f32_16x16x32_f16 v[50:53], v[190:193], v[206:209], 0
	v_mfma_f32_16x16x32_f16 v[46:49], v[198:201], v[206:209], 0
	v_mfma_f32_16x16x32_f16 v[34:37], v[190:193], v[214:217], 0
	v_mfma_f32_16x16x32_f16 v[30:33], v[198:201], v[214:217], 0
	v_mfma_f32_16x16x32_f16 v[18:21], v[190:193], v[222:225], 0
	v_mfma_f32_16x16x32_f16 v[14:17], v[198:201], v[222:225], 0
	v_mfma_f32_16x16x32_f16 v[10:13], v[190:193], v[230:233], 0
	v_mfma_f32_16x16x32_f16 v[6:9], v[198:201], v[230:233], 0
	v_mfma_f32_16x16x32_f16 v[50:53], v[194:197], v[210:213], v[50:53]
	v_mfma_f32_16x16x32_f16 v[46:49], v[202:205], v[210:213], v[46:49]
	v_mfma_f32_16x16x32_f16 v[34:37], v[194:197], v[218:221], v[34:37]
	v_mfma_f32_16x16x32_f16 v[30:33], v[202:205], v[218:221], v[30:33]
	v_mfma_f32_16x16x32_f16 v[18:21], v[194:197], v[226:229], v[18:21]
	v_mfma_f32_16x16x32_f16 v[14:17], v[202:205], v[226:229], v[14:17]
	v_mfma_f32_16x16x32_f16 v[10:13], v[194:197], v[234:237], v[10:13]
	v_mfma_f32_16x16x32_f16 v[6:9], v[202:205], v[234:237], v[6:9]
	s_barrier
	s_add_i32 s48, 0, 0x18000
	v_add_u32_e32 v177, s48, v148
	s_add_i32 s49, 0, 0x1c000
	ds_read_b128 v[152:155], v177
	ds_read_b128 v[178:181], v177 offset:1024
	ds_read_b128 v[182:185], v177 offset:2048
	ds_read_b128 v[186:189], v177 offset:3072
	v_add_u32_e32 v177, s49, v148
	ds_read_b128 v[190:193], v177
	ds_read_b128 v[194:197], v177 offset:1024
	ds_read_b128 v[198:201], v177 offset:2048
	ds_read_b128 v[202:205], v177 offset:3072
	s_add_u32 s26, s26, 0x40000
	s_addc_u32 s27, s27, 0
	s_mov_b32 m0, s31
	v_lshl_add_u64 v[246:247], s[26:27], 0, v[138:139]
	ds_read_b128 v[206:209], v151 offset:32768
	ds_read_b128 v[210:213], v151 offset:33792
	ds_read_b128 v[214:217], v151 offset:34816
	ds_read_b128 v[218:221], v151 offset:35840
	ds_read_b128 v[222:225], v151 offset:36864
	ds_read_b128 v[226:229], v151 offset:37888
	ds_read_b128 v[230:233], v151 offset:38912
	ds_read_b128 v[234:237], v151 offset:39936
	global_load_lds_dwordx4 v[246:247], off
	v_lshl_add_u64 v[246:247], s[26:27], 0, v[134:135]
	s_mov_b32 m0, s38
	s_nop 0
	global_load_lds_dwordx4 v[246:247], off
	s_waitcnt vmcnt(8)
	s_waitcnt lgkmcnt(0)
	s_barrier
	s_waitcnt lgkmcnt(0)
	v_mfma_f32_16x16x32_f16 v[130:133], v[152:155], v[206:209], v[130:133]
	v_mfma_f32_16x16x32_f16 v[126:129], v[182:185], v[206:209], v[126:129]
	v_mfma_f32_16x16x32_f16 v[122:125], v[152:155], v[214:217], v[122:125]
	v_mfma_f32_16x16x32_f16 v[118:121], v[182:185], v[214:217], v[118:121]
	v_mfma_f32_16x16x32_f16 v[106:109], v[152:155], v[222:225], v[106:109]
	v_mfma_f32_16x16x32_f16 v[102:105], v[182:185], v[222:225], v[102:105]
	v_mfma_f32_16x16x32_f16 v[90:93], v[152:155], v[230:233], v[90:93]
	v_mfma_f32_16x16x32_f16 v[86:89], v[182:185], v[230:233], v[86:89]
	v_mfma_f32_16x16x32_f16 v[130:133], v[178:181], v[210:213], v[130:133]
	v_mfma_f32_16x16x32_f16 v[126:129], v[186:189], v[210:213], v[126:129]
	v_mfma_f32_16x16x32_f16 v[122:125], v[178:181], v[218:221], v[122:125]
	v_mfma_f32_16x16x32_f16 v[118:121], v[186:189], v[218:221], v[118:121]
	v_mfma_f32_16x16x32_f16 v[106:109], v[178:181], v[226:229], v[106:109]
	v_mfma_f32_16x16x32_f16 v[102:105], v[186:189], v[226:229], v[102:105]
	v_mfma_f32_16x16x32_f16 v[90:93], v[178:181], v[234:237], v[90:93]
	v_mfma_f32_16x16x32_f16 v[86:89], v[186:189], v[234:237], v[86:89]
	v_mfma_f32_16x16x32_f16 v[114:117], v[190:193], v[206:209], v[114:117]
	v_mfma_f32_16x16x32_f16 v[110:113], v[198:201], v[206:209], v[110:113]
	v_mfma_f32_16x16x32_f16 v[98:101], v[190:193], v[214:217], v[98:101]
	v_mfma_f32_16x16x32_f16 v[94:97], v[198:201], v[214:217], v[94:97]
	v_mfma_f32_16x16x32_f16 v[82:85], v[190:193], v[222:225], v[82:85]
	v_mfma_f32_16x16x32_f16 v[78:81], v[198:201], v[222:225], v[78:81]
	v_mfma_f32_16x16x32_f16 v[74:77], v[190:193], v[230:233], v[74:77]
	v_mfma_f32_16x16x32_f16 v[70:73], v[198:201], v[230:233], v[70:73]
	v_mfma_f32_16x16x32_f16 v[114:117], v[194:197], v[210:213], v[114:117]
	v_mfma_f32_16x16x32_f16 v[110:113], v[202:205], v[210:213], v[110:113]
	v_mfma_f32_16x16x32_f16 v[98:101], v[194:197], v[218:221], v[98:101]
	v_mfma_f32_16x16x32_f16 v[94:97], v[202:205], v[218:221], v[94:97]
	v_mfma_f32_16x16x32_f16 v[82:85], v[194:197], v[226:229], v[82:85]
	v_mfma_f32_16x16x32_f16 v[78:81], v[202:205], v[226:229], v[78:81]
	v_mfma_f32_16x16x32_f16 v[74:77], v[194:197], v[234:237], v[74:77]
	v_mfma_f32_16x16x32_f16 v[70:73], v[202:205], v[234:237], v[70:73]
	s_barrier
; #define STAGE(bufoff, gbase, voff) do { _Pragma("unroll") for (int _i = 0; _i < 2; ++_i) \
;     __builtin_amdgcn_global_load_lds((const unsigned*)((const char*)(gbase) + (voff)[_i]), (LAS unsigned*)(lds + (bufoff) + ldsw + _i * 8192), 16, 0, 0); } while (0)
; #define LDA(dst, b, h) do { _Pragma("unroll") for (int m = 0; m < 4; ++m) _Pragma("unroll") for (int k = 0; k < 2; ++k) dst[m][k] = *(const LAS half8*)(lds + SA(b, h) + aoff + m * 2048 + k * 1024); } while (0)
; #define MMA(ai, bj, At_, Bt_) do { __builtin_amdgcn_s_setprio(1); \
;     _Pragma("unroll") for (int m = 0; m < 4; ++m) _Pragma("unroll") for (int n = 0; n < 2; ++n) _Pragma("unroll") for (int k = 0; k < 2; ++k) \
;       acc[ai][bj][m][n] = MFMA16(Bt_[n][k], At_[m][k], acc[ai][bj][m][n]); \
;     __builtin_amdgcn_s_setprio(0); } while (0)
; #define WAIT_V(n) asm volatile("s_waitcnt vmcnt(" #n ")" ::: "memory")
; #define WAIT_L(n) asm volatile("s_waitcnt lgkmcnt(" #n ")" ::: "memory")
; #define BAR __builtin_amdgcn_s_barrier()
; #define SCHED __builtin_amdgcn_sched_barrier(0)
; template <int EPI>
; DI void gemm_phase(const int wid_s, const h16* __restrict__ A, const h16* __restrict__ Bt, const int N, const int K, const EpiArgs ea) {
;     ...
;       LDA(At, 1, 1); STAGE(SB(1, 0), b3, voffB); STAGE(SB(1, 1), b3 + hstep, voffB); STAGE(SA(1, 0), a3, voffA);
;       WAIT_V(8); WAIT_L(0); BAR; MMA(1, 0, At, B0); MMA(1, 1, At, B1); BAR; SCHED;
;     }
	s_add_i32 s26, s48, s30
	v_lshl_add_u64 v[238:239], v[238:239], 0, s[36:37]
	s_mov_b32 m0, s26
	ds_read_b128 v[206:209], v151 offset:49152
	ds_read_b128 v[210:213], v151 offset:50176
	ds_read_b128 v[214:217], v151 offset:51200
	ds_read_b128 v[218:221], v151 offset:52224
	ds_read_b128 v[222:225], v151 offset:53248
	ds_read_b128 v[226:229], v151 offset:54272
	ds_read_b128 v[230:233], v151 offset:55296
	ds_read_b128 v[234:237], v151 offset:56320
	global_load_lds_dwordx4 v[238:239], off
	s_add_i32 m0, s26, 0x2000
	s_add_u32 s22, s22, 0x40080
	v_lshl_add_u64 v[238:239], v[240:241], 0, s[36:37]
	s_addc_u32 s23, s23, 0
	s_add_i32 s26, s49, s30
	global_load_lds_dwordx4 v[238:239], off
	v_lshl_add_u64 v[238:239], s[22:23], 0, v[0:1]
	s_mov_b32 m0, s26
	s_nop 0
	global_load_lds_dwordx4 v[238:239], off
	v_lshl_add_u64 v[238:239], s[22:23], 0, v[2:3]
	s_add_i32 m0, s26, 0x2000
	s_nop 0
	global_load_lds_dwordx4 v[238:239], off
	v_lshl_add_u64 v[238:239], v[242:243], 0, s[36:37]
	s_mov_b32 m0, s39
	s_nop 0
	global_load_lds_dwordx4 v[238:239], off
	v_lshl_add_u64 v[238:239], v[244:245], 0, s[36:37]
	s_mov_b32 m0, s40
	s_nop 0
	global_load_lds_dwordx4 v[238:239], off
	s_waitcnt vmcnt(8)
	s_waitcnt lgkmcnt(0)
	s_barrier
	s_waitcnt lgkmcnt(0)
	v_mfma_f32_16x16x32_f16 v[66:69], v[152:155], v[206:209], v[66:69]
	v_mfma_f32_16x16x32_f16 v[62:65], v[182:185], v[206:209], v[62:65]
	v_mfma_f32_16x16x32_f16 v[58:61], v[152:155], v[214:217], v[58:61]
	v_mfma_f32_16x16x32_f16 v[54:57], v[182:185], v[214:217], v[54:57]
	v_mfma_f32_16x16x32_f16 v[42:45], v[152:155], v[222:225], v[42:45]
	v_mfma_f32_16x16x32_f16 v[38:41], v[182:185], v[222:225], v[38:41]
	v_mfma_f32_16x16x32_f16 v[26:29], v[152:155], v[230:233], v[26:29]
	v_mfma_f32_16x16x32_f16 v[22:25], v[182:185], v[230:233], v[22:25]
	v_mfma_f32_16x16x32_f16 v[66:69], v[178:181], v[210:213], v[66:69]
	v_mfma_f32_16x16x32_f16 v[62:65], v[186:189], v[210:213], v[62:65]
	v_mfma_f32_16x16x32_f16 v[58:61], v[178:181], v[218:221], v[58:61]
	v_mfma_f32_16x16x32_f16 v[54:57], v[186:189], v[218:221], v[54:57]
	v_mfma_f32_16x16x32_f16 v[42:45], v[178:181], v[226:229], v[42:45]
	v_mfma_f32_16x16x32_f16 v[38:41], v[186:189], v[226:229], v[38:41]
	v_mfma_f32_16x16x32_f16 v[26:29], v[178:181], v[234:237], v[26:29]
	v_mfma_f32_16x16x32_f16 v[22:25], v[186:189], v[234:237], v[22:25]
	v_mfma_f32_16x16x32_f16 v[50:53], v[190:193], v[206:209], v[50:53]
	v_mfma_f32_16x16x32_f16 v[46:49], v[198:201], v[206:209], v[46:49]
	v_mfma_f32_16x16x32_f16 v[34:37], v[190:193], v[214:217], v[34:37]
	v_mfma_f32_16x16x32_f16 v[30:33], v[198:201], v[214:217], v[30:33]
	v_mfma_f32_16x16x32_f16 v[18:21], v[190:193], v[222:225], v[18:21]
	v_mfma_f32_16x16x32_f16 v[14:17], v[198:201], v[222:225], v[14:17]
	v_mfma_f32_16x16x32_f16 v[10:13], v[190:193], v[230:233], v[10:13]
	v_mfma_f32_16x16x32_f16 v[6:9], v[198:201], v[230:233], v[6:9]
	v_mfma_f32_16x16x32_f16 v[50:53], v[194:197], v[210:213], v[50:53]
	v_mfma_f32_16x16x32_f16 v[46:49], v[202:205], v[210:213], v[46:49]
	v_mfma_f32_16x16x32_f16 v[34:37], v[194:197], v[218:221], v[34:37]
	v_mfma_f32_16x16x32_f16 v[30:33], v[202:205], v[218:221], v[30:33]
	v_mfma_f32_16x16x32_f16 v[18:21], v[194:197], v[226:229], v[18:21]
	v_mfma_f32_16x16x32_f16 v[14:17], v[202:205], v[226:229], v[14:17]
	v_mfma_f32_16x16x32_f16 v[10:13], v[194:197], v[234:237], v[10:13]
	v_mfma_f32_16x16x32_f16 v[6:9], v[202:205], v[234:237], v[6:9]
	s_barrier
	s_add_i32 s47, s47, 2
	s_add_u32 s20, s20, 0x100
	s_addc_u32 s21, s21, 0
	s_cmp_gt_u32 s47, 13

; #define BAR __builtin_amdgcn_s_barrier()
; template <int EPI>
; DI void gemm_phase(const int wid_s, const h16* __restrict__ A, const h16* __restrict__ Bt, const int N, const int K, const EpiArgs ea) {
;     ...
;     for (int ai = 0; ai < 2; ++ai)
; #pragma unroll
;       for (int m = 0; m < 4; ++m) {
;         const size_t row = (size_t)(brow + ai * HALF + wr * 64 + m * 16 + fr);
; #pragma unroll
;         for (int bj = 0; bj < 2; ++bj) {
;           const int col0 = bcol + bj * HALF + wc * 32 + 8 * fq;
;           const f32x4 v0 = acc[ai][bj][m][0], v1 = acc[ai][bj][m][1];
;           if (EPI == 0) {
;             half8 o = {(h16)v0[0], (h16)v0[1], (h16)v0[2], (h16)v0[3], (h16)v1[0], (h16)v1[1], (h16)v1[2], (h16)v1[3]};
;             *(half8*)(ea.out + row * LDH + col0) = o;
;     ...
;     if (!has_next) break;
; #pragma unroll
;     for (int a = 0; a < 2; ++a)
; #pragma unroll
;       for (int b = 0; b < 2; ++b)
; #pragma unroll
;         for (int m = 0; m < 4; ++m)
; #pragma unroll
;           for (int n = 0; n < 2; ++n) acc[a][b][m][n] = (f32x4){0.f, 0.f, 0.f, 0.f};
;     L = Ln; brow = nbrow; bcol = nbcol; cA = nA; cB = nB;
;     if (wr == 1) BAR;
.LBB0_389:
	v_or_b32_e32 v144, s14, v150
	v_add_u32_e32 v154, s12, v5
	v_mov_b64_e32 v[146:147], s[28:29]
	v_ashrrev_i32_e32 v145, 31, v144
	v_mad_i64_i32 v[152:153], s[20:21], v154, s3, v[146:147]
	v_cvt_pk_f16_f32 v129, v128, v129
	v_cvt_pk_f16_f32 v128, v126, v127
	v_cvt_pk_f16_f32 v126, v130, v131
	v_lshlrev_b64 v[130:131], 1, v[144:145]
	v_cvt_pk_f16_f32 v127, v132, v133
	v_lshl_add_u64 v[132:133], v[152:153], 0, v[130:131]
	v_cvt_pk_f16_f32 v113, v112, v113
	v_cvt_pk_f16_f32 v112, v110, v111
	v_cvt_pk_f16_f32 v111, v116, v117
	v_cvt_pk_f16_f32 v110, v114, v115
	global_store_dwordx4 v[132:133], v[126:129], off
	global_store_dwordx4 v[132:133], v[110:113], off offset:256
	s_nop 1
	v_add_u32_e32 v110, 16, v154
	v_mad_i64_i32 v[114:115], s[20:21], v110, s3, v[146:147]
	v_cvt_pk_f16_f32 v113, v120, v121
	v_cvt_pk_f16_f32 v112, v118, v119
	v_cvt_pk_f16_f32 v111, v124, v125
	v_cvt_pk_f16_f32 v110, v122, v123
	v_lshl_add_u64 v[114:115], v[114:115], 0, v[130:131]
	v_cvt_pk_f16_f32 v97, v96, v97
	v_cvt_pk_f16_f32 v96, v94, v95
	v_cvt_pk_f16_f32 v95, v100, v101
	v_cvt_pk_f16_f32 v94, v98, v99
	global_store_dwordx4 v[114:115], v[110:113], off
	global_store_dwordx4 v[114:115], v[94:97], off offset:256
	s_nop 1
	v_add_u32_e32 v94, 32, v154
	v_mad_i64_i32 v[98:99], s[20:21], v94, s3, v[146:147]
	v_cvt_pk_f16_f32 v97, v104, v105
	v_cvt_pk_f16_f32 v96, v102, v103
	v_cvt_pk_f16_f32 v95, v108, v109
	v_cvt_pk_f16_f32 v94, v106, v107
	v_lshl_add_u64 v[98:99], v[98:99], 0, v[130:131]
	v_cvt_pk_f16_f32 v81, v80, v81
	v_cvt_pk_f16_f32 v80, v78, v79
	v_cvt_pk_f16_f32 v79, v84, v85
	v_cvt_pk_f16_f32 v78, v82, v83
	global_store_dwordx4 v[98:99], v[94:97], off
	global_store_dwordx4 v[98:99], v[78:81], off offset:256
	s_nop 1
	v_add_u32_e32 v78, 48, v154
	v_mad_i64_i32 v[82:83], s[20:21], v78, s3, v[146:147]
	v_cvt_pk_f16_f32 v81, v88, v89
	v_cvt_pk_f16_f32 v80, v86, v87
	v_cvt_pk_f16_f32 v79, v92, v93
	v_cvt_pk_f16_f32 v78, v90, v91
	v_lshl_add_u64 v[82:83], v[82:83], 0, v[130:131]
	v_cvt_pk_f16_f32 v73, v72, v73
	v_cvt_pk_f16_f32 v72, v70, v71
	v_cvt_pk_f16_f32 v71, v76, v77
	v_cvt_pk_f16_f32 v70, v74, v75
	global_store_dwordx4 v[82:83], v[78:81], off
	global_store_dwordx4 v[82:83], v[70:73], off offset:256
	s_nop 1
	v_add_u32_e32 v70, 0x80, v154
	v_mad_i64_i32 v[70:71], s[20:21], v70, s3, v[146:147]
	v_cvt_pk_f16_f32 v65, v64, v65
	v_cvt_pk_f16_f32 v64, v62, v63
	v_cvt_pk_f16_f32 v63, v68, v69
	v_cvt_pk_f16_f32 v62, v66, v67
	v_lshl_add_u64 v[66:67], v[70:71], 0, v[130:131]
	v_cvt_pk_f16_f32 v49, v48, v49
	v_cvt_pk_f16_f32 v48, v46, v47
	v_cvt_pk_f16_f32 v47, v52, v53
	v_cvt_pk_f16_f32 v46, v50, v51
	global_store_dwordx4 v[66:67], v[62:65], off
	global_store_dwordx4 v[66:67], v[46:49], off offset:256
	s_nop 1
	v_add_u32_e32 v46, 0x90, v154
	v_mad_i64_i32 v[50:51], s[20:21], v46, s3, v[146:147]
	v_cvt_pk_f16_f32 v49, v56, v57
	v_cvt_pk_f16_f32 v48, v54, v55
	v_cvt_pk_f16_f32 v47, v60, v61
	v_cvt_pk_f16_f32 v46, v58, v59
	v_lshl_add_u64 v[50:51], v[50:51], 0, v[130:131]
	v_cvt_pk_f16_f32 v33, v32, v33
	v_cvt_pk_f16_f32 v32, v30, v31
	v_cvt_pk_f16_f32 v31, v36, v37
	v_cvt_pk_f16_f32 v30, v34, v35
	global_store_dwordx4 v[50:51], v[46:49], off
	global_store_dwordx4 v[50:51], v[30:33], off offset:256
	s_nop 1
	v_add_u32_e32 v30, 0xa0, v154
	v_mad_i64_i32 v[34:35], s[20:21], v30, s3, v[146:147]
	v_cvt_pk_f16_f32 v33, v40, v41
	v_cvt_pk_f16_f32 v32, v38, v39
	v_cvt_pk_f16_f32 v31, v44, v45
	v_cvt_pk_f16_f32 v30, v42, v43
	v_lshl_add_u64 v[34:35], v[34:35], 0, v[130:131]
	v_cvt_pk_f16_f32 v17, v16, v17
	v_cvt_pk_f16_f32 v16, v14, v15
	v_cvt_pk_f16_f32 v15, v20, v21
	v_cvt_pk_f16_f32 v14, v18, v19
	global_store_dwordx4 v[34:35], v[30:33], off
	global_store_dwordx4 v[34:35], v[14:17], off offset:256
	s_nop 1
	v_add_u32_e32 v14, 0xb0, v154
	v_mad_i64_i32 v[18:19], s[20:21], v14, s3, v[146:147]
	v_cvt_pk_f16_f32 v17, v24, v25
	v_cvt_pk_f16_f32 v16, v22, v23
	v_cvt_pk_f16_f32 v15, v28, v29
	v_cvt_pk_f16_f32 v14, v26, v27
	v_lshl_add_u64 v[18:19], v[18:19], 0, v[130:131]
	v_cvt_pk_f16_f32 v9, v8, v9
	v_cvt_pk_f16_f32 v8, v6, v7
	v_cvt_pk_f16_f32 v7, v12, v13
	v_cvt_pk_f16_f32 v6, v10, v11
	global_store_dwordx4 v[18:19], v[14:17], off
	global_store_dwordx4 v[18:19], v[6:9], off offset:256
	v_readlane_b32 s48, v249, 37
	v_readlane_b32 s50, v249, 41
	s_andn2_b64 vcc, exec, s[6:7]
	s_mov_b64 s[6:7], -1
	s_movk_i32 s26, 0x1fff
	v_readlane_b32 s49, v249, 38
	v_readlane_b32 s51, v249, 42
	s_cbranch_vccnz .LBB0_382
	s_andn2_b64 vcc, exec, s[0:1]
	s_cbranch_vccnz .LBB0_381
	s_barrier
	s_branch .LBB0_381
